# EpiResid<1> epilogues (4 phases): first-group residual and LN gain/bias loads issued before the row-statistics round trip; producer temps in the statistics registers; rsq chains in place
# speedup vs baseline: 1.0092x; 1.0030x over previous
; __device__ __forceinline__ unsigned cvt_pk_bf16(float lo, float hi) { unsigned r; asm("v_cvt_pk_bf16_f32 %0, %1, %2" : "=v"(r) : "v"(lo), "v"(hi)); return r; }
;     __device__ __forceinline__ void operator()(const f32x4 (&acc)[2][2][4][2], const Unit& u, int wr, int wc, int fr_in, int fq_in) const {
;     ...
;         for (int bj = 0; bj < 2; ++bj) { f32x4 gv[2], bv[2];
;             if constexpr (BASE == 1) {
; #pragma unroll
;                 for (int n = 0; n < 2; ++n) { gv[n] = *(const f32x4*)(lg + col0 + bj * HALF + 4 * n); bv[n] = *(const f32x4*)(lb + col0 + bj * HALF + 4 * n); } }
; #pragma unroll
;             for (int ai = 0; ai < 2; ++ai) {
;                 f32x4 pf[4][2]; u32x4 pb[4];
; #pragma unroll
;                 for (int m = 0; m < 4; ++m) { const size_t off = (size_t)(row0 + ai * HALF + m * 16) * 1024 + col0 + bj * HALF;
;                     if constexpr (BASE == 0) { pf[m][0] = *(const f32x4*)(basef + off); pf[m][1] = *(const f32x4*)(basef + off + 4); } else pb[m] = *(const u32x4*)(baseb + off); }
; #pragma unroll
;                 for (int m = 0; m < 4; ++m) { const size_t off = (size_t)(row0 + ai * HALF + m * 16) * 1024 + col0 + bj * HALF; f32x4 b[2];
;                     if constexpr (BASE == 0) { b[0] = pf[m][0]; b[1] = pf[m][1]; }
;                     else { const u32x4 pw = pb[m]; b[0] = (f32x4){bf_lo(pw.x), bf_hi(pw.x), bf_lo(pw.y), bf_hi(pw.y)}; b[1] = (f32x4){bf_lo(pw.z), bf_hi(pw.z), bf_lo(pw.w), bf_hi(pw.w)}; }
;                     f32x4 z[2];
; #pragma unroll
;                     for (int n = 0; n < 2; ++n) { if constexpr (BASE == 1) b[n] = (b[n] - rst.mu[ai][m]) * rst.rs[ai][m] * gv[n] + bv[n];
;                         z[n] = b[n] * al_ + acc[ai][bj][m][n] * s_; }
;                     u32x4 w; w.x = cvt_pk_bf16(z[0][0], z[0][1]); w.y = cvt_pk_bf16(z[0][2], z[0][3]); w.z = cvt_pk_bf16(z[1][0], z[1][1]); w.w = cvt_pk_bf16(z[1][2], z[1][3]);
;                     *(u32x4*)(zb + off) = w;
;                     const float r0 = bf_lo(w.x), r1 = bf_hi(w.x), r2 = bf_lo(w.y), r3 = bf_hi(w.y), r4 = bf_lo(w.z), r5 = bf_hi(w.z), r6 = bf_lo(w.w), r7 = bf_hi(w.w);
;                     s1[ai][m] += ((r0 + r1) + (r2 + r3)) + ((r4 + r5) + (r6 + r7)); s2[ai][m] += ((r0 * r0 + r1 * r1) + (r2 * r2 + r3 * r3)) + ((r4 * r4 + r5 * r5) + (r6 * r6 + r7 * r7)); }
.LBB0_1175:
	s_lshl_b32 s11, s48, 8
	v_mov_b32_e32 v203, v177
	v_mov_b32_e32 v199, v175
	s_add_i32 s8, s11, s60
	v_mov_b32_e32 v174, 1.0
	v_add_u32_e32 v146, s8, v199
	v_ashrrev_i32_e32 v147, 31, v146
	v_mov_b32_e32 v176, 0x3fb504f3
	v_add_u32_e32 v144, 16, v146
	v_ashrrev_i32_e32 v145, 31, v144
	v_add_u32_e32 v148, 32, v146
	v_ashrrev_i32_e32 v149, 31, v148
	v_add_u32_e32 v150, 48, v146
	v_ashrrev_i32_e32 v151, 31, v150
	v_add_u32_e32 v222, 0x80, v146
	v_ashrrev_i32_e32 v223, 31, v222
	v_add_u32_e32 v226, 0x90, v146
	v_ashrrev_i32_e32 v227, 31, v226
	v_add_u32_e32 v210, 0xa0, v146
	v_ashrrev_i32_e32 v211, 31, v210
	v_add_u32_e32 v212, 0xb0, v146
	v_ashrrev_i32_e32 v213, 31, v212
	s_lshl_b32 s8, s10, 8
	s_or_b32 s8, s8, s61
	v_lshl_add_u32 v152, v203, 3, s8
	v_ashrrev_i32_e32 v153, 31, v152
	v_lshlrev_b64 v[220:221], 1, v[152:153]
	v_lshl_add_u64 v[234:235], s[22:23], 0, v[220:221]
	v_lshlrev_b64 v[232:233], 11, v[146:147]
	v_lshl_add_u64 v[218:219], v[234:235], 0, v[232:233]
	v_lshlrev_b64 v[236:237], 11, v[144:145]
	v_lshl_add_u64 v[224:225], v[234:235], 0, v[236:237]
	v_lshlrev_b64 v[240:241], 11, v[148:149]
	v_lshl_add_u64 v[228:229], v[234:235], 0, v[240:241]
	v_lshlrev_b64 v[238:239], 11, v[150:151]
	v_lshl_add_u64 v[230:231], v[234:235], 0, v[238:239]
	v_and_b32_e32 v181, 0xff, v146
	v_lshlrev_b32_e32 v181, 3, v181
	v_add_u32_e32 v181, 0x22400, v181
	v_and_b32_e32 v208, 0xffffff00, v146
	v_lshlrev_b64 v[128:129], 2, v[152:153]
	v_lshl_add_u64 v[216:217], s[4:5], 0, v[128:129]
	v_lshl_add_u64 v[214:215], s[6:7], 0, v[128:129]
	global_load_dwordx4 v[128:131], v[216:217], off offset:16
	global_load_dwordx4 v[136:139], v[216:217], off
	global_load_dwordx4 v[132:135], v[214:215], off offset:16
	global_load_dwordx4 v[140:143], v[214:215], off
	global_load_dwordx4 v[152:155], v[218:219], off
	global_load_dwordx4 v[144:147], v[224:225], off
	global_load_dwordx4 v[242:245], v[228:229], off
	global_load_dwordx4 v[148:151], v[230:231], off
	v_readfirstlane_b32 s98, v254
	s_nop 0
	s_cmpk_lt_u32 s98, 0x100
	s_cbranch_scc0 .Lrs1_skip
	v_add_u32_e32 v208, v208, v254
	v_mov_b32_e32 v209, 0
	v_lshlrev_b64 v[208:209], 5, v[208:209]
	v_lshl_add_u64 v[208:209], s[24:25], 0, v[208:209]
	global_load_dwordx2 v[204:205], v[208:209], off
	global_load_dwordx2 v[200:201], v[208:209], off offset:8
	global_load_dwordx2 v[196:197], v[208:209], off offset:16
	global_load_dwordx2 v[192:193], v[208:209], off offset:24
	s_waitcnt vmcnt(0)
	v_pk_add_f32 v[196:197], v[196:197], v[192:193]
	v_pk_add_f32 v[204:205], v[204:205], v[200:201]
	s_nop 0
	v_pk_add_f32 v[196:197], v[204:205], v[196:197]
	s_nop 0
	v_pk_mul_f32 v[196:197], v[196:197], s[40:41] op_sel_hi:[1,0]
	v_lshlrev_b32_e32 v188, 3, v254
	v_add_u32_e32 v188, 0x22400, v188
	ds_write_b64 v188, v[196:197]
.Lrs1_skip:
	s_waitcnt vmcnt(0) lgkmcnt(0)
	s_barrier
	ds_read_b64 v[208:209], v181
	ds_read_b64 v[204:205], v181 offset:128
	ds_read_b64 v[200:201], v181 offset:256
	ds_read_b64 v[196:197], v181 offset:384
	ds_read_b64 v[192:193], v181 offset:1024
	ds_read_b64 v[188:189], v181 offset:1152
	ds_read_b64 v[184:185], v181 offset:1280
	ds_read_b64 v[180:181], v181 offset:1408
	s_waitcnt lgkmcnt(0)
	v_fma_f32 v209, -v208, v208, v209
	v_max_f32_e32 v209, 0, v209
	v_add_f32_e32 v209, 0x3727c5ac, v209
	v_rsq_f32_e32 v206, v209
	v_fma_f32 v205, -v204, v204, v205
	v_max_f32_e32 v205, 0, v205
	v_add_f32_e32 v205, 0x3727c5ac, v205
	v_rsq_f32_e32 v202, v205
	v_fma_f32 v201, -v200, v200, v201
	v_max_f32_e32 v201, 0, v201
	v_add_f32_e32 v201, 0x3727c5ac, v201
	v_rsq_f32_e32 v198, v201
	v_fma_f32 v197, -v196, v196, v197
	v_max_f32_e32 v197, 0, v197
	v_add_f32_e32 v197, 0x3727c5ac, v197
	v_rsq_f32_e32 v194, v197
	v_fma_f32 v193, -v192, v192, v193
	v_max_f32_e32 v193, 0, v193
	v_add_f32_e32 v193, 0x3727c5ac, v193
	v_rsq_f32_e32 v190, v193
	v_fma_f32 v189, -v188, v188, v189
	v_max_f32_e32 v189, 0, v189
	v_add_f32_e32 v189, 0x3727c5ac, v189
	v_rsq_f32_e32 v186, v189
	v_fma_f32 v185, -v184, v184, v185
	v_max_f32_e32 v185, 0, v185
	v_add_f32_e32 v185, 0x3727c5ac, v185
	v_rsq_f32_e32 v182, v185
	v_fma_f32 v181, -v180, v180, v181
	v_max_f32_e32 v181, 0, v181
	v_add_f32_e32 v181, 0x3727c5ac, v181
	v_rsq_f32_e32 v178, v181
	s_waitcnt vmcnt(0)
	v_lshlrev_b32_e32 v165, 16, v152
	v_and_b32_e32 v181, 0xffff0000, v152
	v_lshlrev_b32_e32 v152, 16, v153
	v_and_b32_e32 v153, 0xffff0000, v153
	v_lshlrev_b32_e32 v185, 16, v154
	v_and_b32_e32 v189, 0xffff0000, v154
	v_lshlrev_b32_e32 v193, 16, v155
	v_and_b32_e32 v197, 0xffff0000, v155
	v_sub_f32_e32 v153, v153, v208
	v_sub_f32_e32 v152, v152, v208
	v_sub_f32_e32 v155, v181, v208
	v_sub_f32_e32 v154, v165, v208
	v_pk_mul_f32 v[154:155], v[206:207], v[154:155] op_sel_hi:[0,1]
	v_pk_mul_f32 v[152:153], v[206:207], v[152:153] op_sel_hi:[0,1]
	v_pk_fma_f32 v[152:153], v[138:139], v[152:153], v[142:143]
	v_pk_fma_f32 v[154:155], v[136:137], v[154:155], v[140:141]
	v_pk_mul_f32 v[152:153], v[176:177], v[152:153] op_sel_hi:[0,1]
	v_pk_mul_f32 v[154:155], v[176:177], v[154:155] op_sel_hi:[0,1]
	v_pk_fma_f32 v[126:127], v[126:127], v[174:175], v[152:153] op_sel_hi:[1,0,1]
	v_pk_fma_f32 v[124:125], v[124:125], v[174:175], v[154:155] op_sel_hi:[1,0,1]
	v_sub_f32_e32 v153, v197, v208
	v_sub_f32_e32 v152, v193, v208
	v_sub_f32_e32 v155, v189, v208
	v_sub_f32_e32 v154, v185, v208
	v_pk_mul_f32 v[154:155], v[206:207], v[154:155] op_sel_hi:[0,1]
	v_pk_mul_f32 v[152:153], v[206:207], v[152:153] op_sel_hi:[0,1]
	v_pk_fma_f32 v[152:153], v[130:131], v[152:153], v[134:135]
	v_pk_fma_f32 v[154:155], v[128:129], v[154:155], v[132:133]
	v_pk_mul_f32 v[152:153], v[176:177], v[152:153] op_sel_hi:[0,1]
; __device__ __forceinline__ unsigned cvt_pk_bf16(float lo, float hi) { unsigned r; asm("v_cvt_pk_bf16_f32 %0, %1, %2" : "=v"(r) : "v"(lo), "v"(hi)); return r; }
; __device__ __forceinline__ float bf_lo(unsigned w) { return __uint_as_float(w << 16); }
; __device__ __forceinline__ float bf_hi(unsigned w) { return __uint_as_float(w & 0xffff0000u); }
;     __device__ __forceinline__ void operator()(const f32x4 (&acc)[2][2][4][2], const Unit& u, int wr, int wc, int fr_in, int fq_in) const {
;     ...
;             for (int ai = 0; ai < 2; ++ai) {
;                 f32x4 pf[4][2]; u32x4 pb[4];
; #pragma unroll
;                 for (int m = 0; m < 4; ++m) { const size_t off = (size_t)(row0 + ai * HALF + m * 16) * 1024 + col0 + bj * HALF;
;                     if constexpr (BASE == 0) { pf[m][0] = *(const f32x4*)(basef + off); pf[m][1] = *(const f32x4*)(basef + off + 4); } else pb[m] = *(const u32x4*)(baseb + off); }
; #pragma unroll
;                 for (int m = 0; m < 4; ++m) { const size_t off = (size_t)(row0 + ai * HALF + m * 16) * 1024 + col0 + bj * HALF; f32x4 b[2];
;                     if constexpr (BASE == 0) { b[0] = pf[m][0]; b[1] = pf[m][1]; }
;                     else { const u32x4 pw = pb[m]; b[0] = (f32x4){bf_lo(pw.x), bf_hi(pw.x), bf_lo(pw.y), bf_hi(pw.y)}; b[1] = (f32x4){bf_lo(pw.z), bf_hi(pw.z), bf_lo(pw.w), bf_hi(pw.w)}; }
;                     f32x4 z[2];
; #pragma unroll
;                     for (int n = 0; n < 2; ++n) { if constexpr (BASE == 1) b[n] = (b[n] - rst.mu[ai][m]) * rst.rs[ai][m] * gv[n] + bv[n];
;                         z[n] = b[n] * al_ + acc[ai][bj][m][n] * s_; }
;                     u32x4 w; w.x = cvt_pk_bf16(z[0][0], z[0][1]); w.y = cvt_pk_bf16(z[0][2], z[0][3]); w.z = cvt_pk_bf16(z[1][0], z[1][1]); w.w = cvt_pk_bf16(z[1][2], z[1][3]);
;                     *(u32x4*)(zb + off) = w;
;                     const float r0 = bf_lo(w.x), r1 = bf_hi(w.x), r2 = bf_lo(w.y), r3 = bf_hi(w.y), r4 = bf_lo(w.z), r5 = bf_hi(w.z), r6 = bf_lo(w.w), r7 = bf_hi(w.w);
;                     s1[ai][m] += ((r0 + r1) + (r2 + r3)) + ((r4 + r5) + (r6 + r7)); s2[ai][m] += ((r0 * r0 + r1 * r1) + (r2 * r2 + r3 * r3)) + ((r4 * r4 + r5 * r5) + (r6 * r6 + r7 * r7)); }
	v_pk_mul_f32 v[154:155], v[176:177], v[154:155] op_sel_hi:[0,1]
	v_pk_fma_f32 v[152:153], v[122:123], v[174:175], v[152:153] op_sel_hi:[1,0,1]
	v_pk_fma_f32 v[122:123], v[120:121], v[174:175], v[154:155] op_sel_hi:[1,0,1]
	v_cvt_pk_bf16_f32 v120, v124, v125
	v_lshl_add_u64 v[124:125], s[22:23], 0, v[232:233]
	v_cvt_pk_bf16_f32 v121, v126, v127
	v_lshl_add_u64 v[232:233], v[124:125], 0, v[220:221]
	v_lshlrev_b32_e32 v125, 16, v144
	v_and_b32_e32 v127, 0xffff0000, v144
	v_lshlrev_b32_e32 v144, 16, v145
	v_and_b32_e32 v145, 0xffff0000, v145
	v_cvt_pk_bf16_f32 v122, v122, v123
	v_cvt_pk_bf16_f32 v123, v152, v153
	v_lshlrev_b32_e32 v153, 16, v146
	v_and_b32_e32 v155, 0xffff0000, v146
	v_lshlrev_b32_e32 v165, 16, v147
	v_and_b32_e32 v181, 0xffff0000, v147
	v_sub_f32_e32 v145, v145, v204
	v_sub_f32_e32 v144, v144, v204
	v_sub_f32_e32 v147, v127, v204
	v_sub_f32_e32 v146, v125, v204
	v_pk_mul_f32 v[146:147], v[202:203], v[146:147] op_sel_hi:[0,1]
	v_pk_mul_f32 v[144:145], v[202:203], v[144:145] op_sel_hi:[0,1]
	v_pk_fma_f32 v[144:145], v[138:139], v[144:145], v[142:143]
	v_pk_fma_f32 v[146:147], v[136:137], v[146:147], v[140:141]
	v_pk_mul_f32 v[144:145], v[176:177], v[144:145] op_sel_hi:[0,1]
	v_pk_mul_f32 v[146:147], v[176:177], v[146:147] op_sel_hi:[0,1]
	v_pk_fma_f32 v[118:119], v[118:119], v[174:175], v[144:145] op_sel_hi:[1,0,1]
	v_pk_fma_f32 v[116:117], v[116:117], v[174:175], v[146:147] op_sel_hi:[1,0,1]
	v_sub_f32_e32 v145, v181, v204
	v_sub_f32_e32 v144, v165, v204
	v_sub_f32_e32 v147, v155, v204
	v_sub_f32_e32 v146, v153, v204
	v_pk_mul_f32 v[146:147], v[202:203], v[146:147] op_sel_hi:[0,1]
	v_pk_mul_f32 v[144:145], v[202:203], v[144:145] op_sel_hi:[0,1]
	v_pk_fma_f32 v[144:145], v[130:131], v[144:145], v[134:135]
	v_pk_fma_f32 v[146:147], v[128:129], v[146:147], v[132:133]
	v_pk_mul_f32 v[144:145], v[176:177], v[144:145] op_sel_hi:[0,1]
	v_pk_mul_f32 v[146:147], v[176:177], v[146:147] op_sel_hi:[0,1]
	v_pk_fma_f32 v[144:145], v[114:115], v[174:175], v[144:145] op_sel_hi:[1,0,1]
	v_pk_fma_f32 v[114:115], v[112:113], v[174:175], v[146:147] op_sel_hi:[1,0,1]
	v_cvt_pk_bf16_f32 v113, v118, v119
	v_lshlrev_b32_e32 v125, 16, v242
	v_and_b32_e32 v127, 0xffff0000, v242
	v_lshlrev_b32_e32 v118, 16, v243
	v_and_b32_e32 v119, 0xffff0000, v243
	v_cvt_pk_bf16_f32 v114, v114, v115
	v_cvt_pk_bf16_f32 v115, v144, v145
	v_sub_f32_e32 v119, v119, v200
	v_sub_f32_e32 v118, v118, v200
	v_sub_f32_e32 v145, v127, v200
	v_sub_f32_e32 v144, v125, v200
	v_pk_mul_f32 v[144:145], v[198:199], v[144:145] op_sel_hi:[0,1]
	v_pk_mul_f32 v[118:119], v[198:199], v[118:119] op_sel_hi:[0,1]
	v_pk_fma_f32 v[118:119], v[138:139], v[118:119], v[142:143]
	v_pk_fma_f32 v[144:145], v[136:137], v[144:145], v[140:141]
	v_lshlrev_b32_e32 v146, 16, v244
	v_and_b32_e32 v147, 0xffff0000, v244
	v_lshlrev_b32_e32 v153, 16, v245
	v_and_b32_e32 v155, 0xffff0000, v245
	v_pk_mul_f32 v[144:145], v[176:177], v[144:145] op_sel_hi:[0,1]
	v_pk_mul_f32 v[118:119], v[176:177], v[118:119] op_sel_hi:[0,1]
	v_pk_fma_f32 v[110:111], v[110:111], v[174:175], v[118:119] op_sel_hi:[1,0,1]
	v_pk_fma_f32 v[108:109], v[108:109], v[174:175], v[144:145] op_sel_hi:[1,0,1]
	v_sub_f32_e32 v119, v155, v200
	v_sub_f32_e32 v118, v153, v200
	v_sub_f32_e32 v145, v147, v200
	v_sub_f32_e32 v144, v146, v200
	v_pk_mul_f32 v[144:145], v[198:199], v[144:145] op_sel_hi:[0,1]
	v_pk_mul_f32 v[118:119], v[198:199], v[118:119] op_sel_hi:[0,1]
	v_pk_fma_f32 v[118:119], v[130:131], v[118:119], v[134:135]
	v_pk_fma_f32 v[144:145], v[128:129], v[144:145], v[132:133]
	v_pk_mul_f32 v[118:119], v[176:177], v[118:119] op_sel_hi:[0,1]
	v_pk_mul_f32 v[144:145], v[176:177], v[144:145] op_sel_hi:[0,1]
	v_pk_fma_f32 v[118:119], v[106:107], v[174:175], v[118:119] op_sel_hi:[1,0,1]
	v_pk_fma_f32 v[106:107], v[104:105], v[174:175], v[144:145] op_sel_hi:[1,0,1]
	v_cvt_pk_bf16_f32 v105, v110, v111
	v_lshlrev_b32_e32 v110, 16, v149
	v_cvt_pk_bf16_f32 v106, v106, v107
	v_cvt_pk_bf16_f32 v107, v118, v119
	v_lshlrev_b32_e32 v118, 16, v148
	v_and_b32_e32 v119, 0xffff0000, v148
	v_and_b32_e32 v111, 0xffff0000, v149
	v_sub_f32_e32 v111, v111, v196
	v_sub_f32_e32 v110, v110, v196
	v_sub_f32_e32 v119, v119, v196
	v_sub_f32_e32 v118, v118, v196
	v_pk_mul_f32 v[118:119], v[194:195], v[118:119] op_sel_hi:[0,1]
	v_pk_mul_f32 v[110:111], v[194:195], v[110:111] op_sel_hi:[0,1]
	v_pk_fma_f32 v[110:111], v[138:139], v[110:111], v[142:143]
	v_pk_fma_f32 v[118:119], v[136:137], v[118:119], v[140:141]
	v_lshlrev_b32_e32 v125, 16, v150
	v_and_b32_e32 v127, 0xffff0000, v150
	v_lshlrev_b32_e32 v144, 16, v151
	v_and_b32_e32 v145, 0xffff0000, v151
	v_pk_mul_f32 v[118:119], v[176:177], v[118:119] op_sel_hi:[0,1]
	v_pk_mul_f32 v[110:111], v[176:177], v[110:111] op_sel_hi:[0,1]
	v_pk_fma_f32 v[102:103], v[102:103], v[174:175], v[110:111] op_sel_hi:[1,0,1]
	v_pk_fma_f32 v[100:101], v[100:101], v[174:175], v[118:119] op_sel_hi:[1,0,1]
	v_sub_f32_e32 v111, v145, v196
	v_sub_f32_e32 v110, v144, v196
	v_sub_f32_e32 v119, v127, v196
	v_sub_f32_e32 v118, v125, v196
	v_pk_mul_f32 v[118:119], v[194:195], v[118:119] op_sel_hi:[0,1]
	v_pk_mul_f32 v[110:111], v[194:195], v[110:111] op_sel_hi:[0,1]
	v_pk_fma_f32 v[110:111], v[130:131], v[110:111], v[134:135]
	v_pk_fma_f32 v[118:119], v[128:129], v[118:119], v[132:133]
	v_pk_mul_f32 v[110:111], v[176:177], v[110:111] op_sel_hi:[0,1]
	v_pk_mul_f32 v[118:119], v[176:177], v[118:119] op_sel_hi:[0,1]
	v_cvt_pk_bf16_f32 v112, v116, v117
	v_lshl_add_u64 v[116:117], s[22:23], 0, v[236:237]
	v_cvt_pk_bf16_f32 v104, v108, v109
	v_lshl_add_u64 v[108:109], s[22:23], 0, v[240:241]
	v_pk_fma_f32 v[110:111], v[98:99], v[174:175], v[110:111] op_sel_hi:[1,0,1]
	v_pk_fma_f32 v[98:99], v[96:97], v[174:175], v[118:119] op_sel_hi:[1,0,1]
	v_cvt_pk_bf16_f32 v96, v100, v101
	v_lshl_add_u64 v[100:101], s[22:23], 0, v[238:239]
	v_lshl_add_u64 v[116:117], v[116:117], 0, v[220:221]
	v_lshl_add_u64 v[108:109], v[108:109], 0, v[220:221]
	v_lshl_add_u64 v[100:101], v[100:101], 0, v[220:221]
	global_store_dwordx4 v[232:233], v[120:123], off
	global_store_dwordx4 v[116:117], v[112:115], off
	global_store_dwordx4 v[108:109], v[104:107], off
	v_cvt_pk_bf16_f32 v97, v102, v103
	v_cvt_pk_bf16_f32 v98, v98, v99
	v_cvt_pk_bf16_f32 v99, v110, v111
	global_store_dwordx4 v[100:101], v[96:99], off
	v_lshlrev_b64 v[144:145], 11, v[222:223]
	v_lshl_add_u64 v[102:103], v[234:235], 0, v[144:145]
	global_load_dwordx4 v[236:239], v[102:103], off
	v_lshlrev_b64 v[146:147], 11, v[226:227]
	v_lshl_add_u64 v[110:111], v[234:235], 0, v[146:147]
	global_load_dwordx4 v[240:243], v[110:111], off
	v_lshlrev_b64 v[150:151], 11, v[210:211]
	v_lshl_add_u64 v[148:149], v[234:235], 0, v[150:151]
	global_load_dwordx4 v[244:247], v[148:149], off
	v_lshlrev_b64 v[210:211], 11, v[212:213]
	v_lshl_add_u64 v[118:119], v[234:235], 0, v[210:211]
	global_load_dwordx4 v[248:251], v[118:119], off
	v_and_b32_e32 v154, 0xffff0000, v120
	v_lshlrev_b32_e32 v152, 16, v121
	v_and_b32_e32 v126, 0xffff0000, v122
	v_lshlrev_b32_e32 v124, 16, v123
	s_waitcnt vmcnt(0)
; __device__ __forceinline__ unsigned cvt_pk_bf16(float lo, float hi) { unsigned r; asm("v_cvt_pk_bf16_f32 %0, %1, %2" : "=v"(r) : "v"(lo), "v"(hi)); return r; }
; __device__ __forceinline__ float bf_lo(unsigned w) { return __uint_as_float(w << 16); }
; __device__ __forceinline__ float bf_hi(unsigned w) { return __uint_as_float(w & 0xffff0000u); }
;     __device__ __forceinline__ void operator()(const f32x4 (&acc)[2][2][4][2], const Unit& u, int wr, int wc, int fr_in, int fq_in) const {
;     ...
;             for (int ai = 0; ai < 2; ++ai) {
;                 f32x4 pf[4][2]; u32x4 pb[4];
; #pragma unroll
;                 for (int m = 0; m < 4; ++m) { const size_t off = (size_t)(row0 + ai * HALF + m * 16) * 1024 + col0 + bj * HALF;
;                     if constexpr (BASE == 0) { pf[m][0] = *(const f32x4*)(basef + off); pf[m][1] = *(const f32x4*)(basef + off + 4); } else pb[m] = *(const u32x4*)(baseb + off); }
; #pragma unroll
;                 for (int m = 0; m < 4; ++m) { const size_t off = (size_t)(row0 + ai * HALF + m * 16) * 1024 + col0 + bj * HALF; f32x4 b[2];
;                     if constexpr (BASE == 0) { b[0] = pf[m][0]; b[1] = pf[m][1]; }
;                     else { const u32x4 pw = pb[m]; b[0] = (f32x4){bf_lo(pw.x), bf_hi(pw.x), bf_lo(pw.y), bf_hi(pw.y)}; b[1] = (f32x4){bf_lo(pw.z), bf_hi(pw.z), bf_lo(pw.w), bf_hi(pw.w)}; }
;                     f32x4 z[2];
; #pragma unroll
;                     for (int n = 0; n < 2; ++n) { if constexpr (BASE == 1) b[n] = (b[n] - rst.mu[ai][m]) * rst.rs[ai][m] * gv[n] + bv[n];
;                         z[n] = b[n] * al_ + acc[ai][bj][m][n] * s_; }
;                     u32x4 w; w.x = cvt_pk_bf16(z[0][0], z[0][1]); w.y = cvt_pk_bf16(z[0][2], z[0][3]); w.z = cvt_pk_bf16(z[1][0], z[1][1]); w.w = cvt_pk_bf16(z[1][2], z[1][3]);
;                     *(u32x4*)(zb + off) = w;
;                     const float r0 = bf_lo(w.x), r1 = bf_hi(w.x), r2 = bf_lo(w.y), r3 = bf_hi(w.y), r4 = bf_lo(w.z), r5 = bf_hi(w.z), r6 = bf_lo(w.w), r7 = bf_hi(w.w);
;                     s1[ai][m] += ((r0 + r1) + (r2 + r3)) + ((r4 + r5) + (r6 + r7)); s2[ai][m] += ((r0 * r0 + r1 * r1) + (r2 * r2 + r3 * r3)) + ((r4 * r4 + r5 * r5) + (r6 * r6 + r7 * r7)); }
	v_lshlrev_b32_e32 v125, 16, v236
	v_and_b32_e32 v127, 0xffff0000, v236
	v_lshlrev_b32_e32 v153, 16, v237
	v_and_b32_e32 v155, 0xffff0000, v237
	v_sub_f32_e32 v213, v155, v192
	v_sub_f32_e32 v212, v153, v192
	v_sub_f32_e32 v223, v127, v192
	v_sub_f32_e32 v222, v125, v192
	v_pk_mul_f32 v[222:223], v[190:191], v[222:223] op_sel_hi:[0,1]
	v_pk_mul_f32 v[212:213], v[190:191], v[212:213] op_sel_hi:[0,1]
	v_pk_fma_f32 v[212:213], v[138:139], v[212:213], v[142:143]
	v_pk_fma_f32 v[222:223], v[136:137], v[222:223], v[140:141]
	v_lshlrev_b32_e32 v165, 16, v238
	v_and_b32_e32 v181, 0xffff0000, v238
	v_lshlrev_b32_e32 v185, 16, v239
	v_and_b32_e32 v189, 0xffff0000, v239
	v_pk_mul_f32 v[222:223], v[176:177], v[222:223] op_sel_hi:[0,1]
	v_pk_mul_f32 v[212:213], v[176:177], v[212:213] op_sel_hi:[0,1]
	v_pk_fma_f32 v[94:95], v[94:95], v[174:175], v[212:213] op_sel_hi:[1,0,1]
	v_pk_fma_f32 v[92:93], v[92:93], v[174:175], v[222:223] op_sel_hi:[1,0,1]
	v_sub_f32_e32 v213, v189, v192
	v_sub_f32_e32 v212, v185, v192
	v_sub_f32_e32 v223, v181, v192
	v_sub_f32_e32 v222, v165, v192
	v_pk_mul_f32 v[222:223], v[190:191], v[222:223] op_sel_hi:[0,1]
	v_pk_mul_f32 v[212:213], v[190:191], v[212:213] op_sel_hi:[0,1]
	v_pk_fma_f32 v[212:213], v[130:131], v[212:213], v[134:135]
	v_pk_fma_f32 v[222:223], v[128:129], v[222:223], v[132:133]
	v_pk_mul_f32 v[212:213], v[176:177], v[212:213] op_sel_hi:[0,1]
	v_pk_mul_f32 v[222:223], v[176:177], v[222:223] op_sel_hi:[0,1]
	v_pk_fma_f32 v[212:213], v[90:91], v[174:175], v[212:213] op_sel_hi:[1,0,1]
	v_pk_fma_f32 v[90:91], v[88:89], v[174:175], v[222:223] op_sel_hi:[1,0,1]
	v_cvt_pk_bf16_f32 v88, v92, v93
	v_lshl_add_u64 v[92:93], s[22:23], 0, v[144:145]
	v_cvt_pk_bf16_f32 v89, v94, v95
	v_lshl_add_u64 v[144:145], v[92:93], 0, v[220:221]
	v_lshlrev_b32_e32 v94, 16, v240
	v_and_b32_e32 v95, 0xffff0000, v240
	v_lshlrev_b32_e32 v92, 16, v241
	v_and_b32_e32 v93, 0xffff0000, v241
	v_sub_f32_e32 v93, v93, v188
	v_sub_f32_e32 v92, v92, v188
	v_sub_f32_e32 v95, v95, v188
	v_sub_f32_e32 v94, v94, v188
	v_pk_mul_f32 v[94:95], v[186:187], v[94:95] op_sel_hi:[0,1]
	v_pk_mul_f32 v[92:93], v[186:187], v[92:93] op_sel_hi:[0,1]
	v_pk_fma_f32 v[92:93], v[138:139], v[92:93], v[142:143]
	v_pk_fma_f32 v[94:95], v[136:137], v[94:95], v[140:141]
	v_lshlrev_b32_e32 v125, 16, v242
	v_and_b32_e32 v127, 0xffff0000, v242
	v_lshlrev_b32_e32 v153, 16, v243
	v_and_b32_e32 v155, 0xffff0000, v243
	v_pk_mul_f32 v[94:95], v[176:177], v[94:95] op_sel_hi:[0,1]
	v_pk_mul_f32 v[92:93], v[176:177], v[92:93] op_sel_hi:[0,1]
	v_pk_fma_f32 v[86:87], v[86:87], v[174:175], v[92:93] op_sel_hi:[1,0,1]
	v_pk_fma_f32 v[84:85], v[84:85], v[174:175], v[94:95] op_sel_hi:[1,0,1]
	v_sub_f32_e32 v93, v155, v188
	v_sub_f32_e32 v92, v153, v188
	v_sub_f32_e32 v95, v127, v188
	v_sub_f32_e32 v94, v125, v188
	v_pk_mul_f32 v[94:95], v[186:187], v[94:95] op_sel_hi:[0,1]
	v_pk_mul_f32 v[92:93], v[186:187], v[92:93] op_sel_hi:[0,1]
	v_pk_fma_f32 v[92:93], v[130:131], v[92:93], v[134:135]
	v_pk_fma_f32 v[94:95], v[128:129], v[94:95], v[132:133]
	v_pk_mul_f32 v[92:93], v[176:177], v[92:93] op_sel_hi:[0,1]
	v_pk_mul_f32 v[94:95], v[176:177], v[94:95] op_sel_hi:[0,1]
	v_pk_fma_f32 v[92:93], v[82:83], v[174:175], v[92:93] op_sel_hi:[1,0,1]
	v_pk_fma_f32 v[82:83], v[80:81], v[174:175], v[94:95] op_sel_hi:[1,0,1]
	v_cvt_pk_bf16_f32 v80, v84, v85
	v_lshl_add_u64 v[84:85], s[22:23], 0, v[146:147]
	v_cvt_pk_bf16_f32 v81, v86, v87
	v_lshl_add_u64 v[146:147], v[84:85], 0, v[220:221]
	v_lshlrev_b32_e32 v86, 16, v244
	v_and_b32_e32 v87, 0xffff0000, v244
	v_lshlrev_b32_e32 v84, 16, v245
	v_and_b32_e32 v85, 0xffff0000, v245
	v_sub_f32_e32 v85, v85, v184
	v_sub_f32_e32 v84, v84, v184
	v_sub_f32_e32 v87, v87, v184
	v_sub_f32_e32 v86, v86, v184
	v_pk_mul_f32 v[86:87], v[182:183], v[86:87] op_sel_hi:[0,1]
	v_pk_mul_f32 v[84:85], v[182:183], v[84:85] op_sel_hi:[0,1]
	v_pk_fma_f32 v[84:85], v[138:139], v[84:85], v[142:143]
	v_pk_fma_f32 v[86:87], v[136:137], v[86:87], v[140:141]
	v_cvt_pk_bf16_f32 v82, v82, v83
	v_cvt_pk_bf16_f32 v83, v92, v93
	v_lshlrev_b32_e32 v92, 16, v246
	v_and_b32_e32 v93, 0xffff0000, v246
	v_lshlrev_b32_e32 v94, 16, v247
	v_and_b32_e32 v95, 0xffff0000, v247
	v_pk_mul_f32 v[86:87], v[176:177], v[86:87] op_sel_hi:[0,1]
	v_pk_mul_f32 v[84:85], v[176:177], v[84:85] op_sel_hi:[0,1]
	v_pk_fma_f32 v[78:79], v[78:79], v[174:175], v[84:85] op_sel_hi:[1,0,1]
	v_pk_fma_f32 v[76:77], v[76:77], v[174:175], v[86:87] op_sel_hi:[1,0,1]
	v_sub_f32_e32 v85, v95, v184
	v_sub_f32_e32 v84, v94, v184
	v_sub_f32_e32 v87, v93, v184
	v_sub_f32_e32 v86, v92, v184
	v_pk_mul_f32 v[86:87], v[182:183], v[86:87] op_sel_hi:[0,1]
	v_pk_mul_f32 v[84:85], v[182:183], v[84:85] op_sel_hi:[0,1]
	v_pk_fma_f32 v[84:85], v[130:131], v[84:85], v[134:135]
	v_pk_fma_f32 v[86:87], v[128:129], v[86:87], v[132:133]
	v_pk_mul_f32 v[84:85], v[176:177], v[84:85] op_sel_hi:[0,1]
	v_pk_mul_f32 v[86:87], v[176:177], v[86:87] op_sel_hi:[0,1]
	v_pk_fma_f32 v[84:85], v[74:75], v[174:175], v[84:85] op_sel_hi:[1,0,1]
	v_pk_fma_f32 v[74:75], v[72:73], v[174:175], v[86:87] op_sel_hi:[1,0,1]
	v_cvt_pk_bf16_f32 v72, v76, v77
	v_lshl_add_u64 v[76:77], s[22:23], 0, v[150:151]
	v_cvt_pk_bf16_f32 v73, v78, v79
	v_lshl_add_u64 v[150:151], v[76:77], 0, v[220:221]
	v_lshlrev_b32_e32 v78, 16, v248
	v_and_b32_e32 v79, 0xffff0000, v248
	v_lshlrev_b32_e32 v76, 16, v249
	v_and_b32_e32 v77, 0xffff0000, v249
	v_sub_f32_e32 v77, v77, v180
	v_sub_f32_e32 v76, v76, v180
	v_sub_f32_e32 v79, v79, v180
	v_sub_f32_e32 v78, v78, v180
	v_pk_mul_f32 v[78:79], v[178:179], v[78:79] op_sel_hi:[0,1]
	v_pk_mul_f32 v[76:77], v[178:179], v[76:77] op_sel_hi:[0,1]
; __device__ __forceinline__ unsigned cvt_pk_bf16(float lo, float hi) { unsigned r; asm("v_cvt_pk_bf16_f32 %0, %1, %2" : "=v"(r) : "v"(lo), "v"(hi)); return r; }
;     __device__ __forceinline__ void operator()(const f32x4 (&acc)[2][2][4][2], const Unit& u, int wr, int wc, int fr_in, int fq_in) const {
;     ...
;         for (int bj = 0; bj < 2; ++bj) { f32x4 gv[2], bv[2];
;             if constexpr (BASE == 1) {
; #pragma unroll
;                 for (int n = 0; n < 2; ++n) { gv[n] = *(const f32x4*)(lg + col0 + bj * HALF + 4 * n); bv[n] = *(const f32x4*)(lb + col0 + bj * HALF + 4 * n); } }
; #pragma unroll
;             for (int ai = 0; ai < 2; ++ai) {
;                 f32x4 pf[4][2]; u32x4 pb[4];
; #pragma unroll
;                 for (int m = 0; m < 4; ++m) { const size_t off = (size_t)(row0 + ai * HALF + m * 16) * 1024 + col0 + bj * HALF;
;                     if constexpr (BASE == 0) { pf[m][0] = *(const f32x4*)(basef + off); pf[m][1] = *(const f32x4*)(basef + off + 4); } else pb[m] = *(const u32x4*)(baseb + off); }
; #pragma unroll
;                 for (int m = 0; m < 4; ++m) { const size_t off = (size_t)(row0 + ai * HALF + m * 16) * 1024 + col0 + bj * HALF; f32x4 b[2];
;                     if constexpr (BASE == 0) { b[0] = pf[m][0]; b[1] = pf[m][1]; }
;                     else { const u32x4 pw = pb[m]; b[0] = (f32x4){bf_lo(pw.x), bf_hi(pw.x), bf_lo(pw.y), bf_hi(pw.y)}; b[1] = (f32x4){bf_lo(pw.z), bf_hi(pw.z), bf_lo(pw.w), bf_hi(pw.w)}; }
;                     f32x4 z[2];
; #pragma unroll
;                     for (int n = 0; n < 2; ++n) { if constexpr (BASE == 1) b[n] = (b[n] - rst.mu[ai][m]) * rst.rs[ai][m] * gv[n] + bv[n];
;                         z[n] = b[n] * al_ + acc[ai][bj][m][n] * s_; }
;                     u32x4 w; w.x = cvt_pk_bf16(z[0][0], z[0][1]); w.y = cvt_pk_bf16(z[0][2], z[0][3]); w.z = cvt_pk_bf16(z[1][0], z[1][1]); w.w = cvt_pk_bf16(z[1][2], z[1][3]);
;                     *(u32x4*)(zb + off) = w;
;                     const float r0 = bf_lo(w.x), r1 = bf_hi(w.x), r2 = bf_lo(w.y), r3 = bf_hi(w.y), r4 = bf_lo(w.z), r5 = bf_hi(w.z), r6 = bf_lo(w.w), r7 = bf_hi(w.w);
;                     s1[ai][m] += ((r0 + r1) + (r2 + r3)) + ((r4 + r5) + (r6 + r7)); s2[ai][m] += ((r0 * r0 + r1 * r1) + (r2 * r2 + r3 * r3)) + ((r4 * r4 + r5 * r5) + (r6 * r6 + r7 * r7)); }
	v_pk_fma_f32 v[76:77], v[138:139], v[76:77], v[142:143]
	v_pk_fma_f32 v[78:79], v[136:137], v[78:79], v[140:141]
	v_cvt_pk_bf16_f32 v74, v74, v75
	v_cvt_pk_bf16_f32 v75, v84, v85
	v_lshlrev_b32_e32 v84, 16, v250
	v_and_b32_e32 v85, 0xffff0000, v250
	v_lshlrev_b32_e32 v86, 16, v251
	v_and_b32_e32 v87, 0xffff0000, v251
	v_pk_mul_f32 v[78:79], v[176:177], v[78:79] op_sel_hi:[0,1]
	v_pk_mul_f32 v[76:77], v[176:177], v[76:77] op_sel_hi:[0,1]
	v_pk_fma_f32 v[70:71], v[70:71], v[174:175], v[76:77] op_sel_hi:[1,0,1]
	v_pk_fma_f32 v[68:69], v[68:69], v[174:175], v[78:79] op_sel_hi:[1,0,1]
	v_sub_f32_e32 v77, v87, v180
	v_sub_f32_e32 v76, v86, v180
	v_sub_f32_e32 v79, v85, v180
	v_sub_f32_e32 v78, v84, v180
	v_pk_mul_f32 v[78:79], v[178:179], v[78:79] op_sel_hi:[0,1]
	v_pk_mul_f32 v[76:77], v[178:179], v[76:77] op_sel_hi:[0,1]
	v_pk_fma_f32 v[76:77], v[130:131], v[76:77], v[134:135]
	v_pk_fma_f32 v[78:79], v[128:129], v[78:79], v[132:133]
	v_pk_mul_f32 v[76:77], v[176:177], v[76:77] op_sel_hi:[0,1]
	v_pk_mul_f32 v[78:79], v[176:177], v[78:79] op_sel_hi:[0,1]
	v_pk_fma_f32 v[76:77], v[66:67], v[174:175], v[76:77] op_sel_hi:[1,0,1]
	v_pk_fma_f32 v[66:67], v[64:65], v[174:175], v[78:79] op_sel_hi:[1,0,1]
	v_cvt_pk_bf16_f32 v64, v68, v69
	v_lshl_add_u64 v[68:69], s[22:23], 0, v[210:211]
	v_lshl_add_u64 v[128:129], v[68:69], 0, v[220:221]
	v_cvt_pk_bf16_f32 v90, v90, v91
	v_cvt_pk_bf16_f32 v91, v212, v213
	global_store_dwordx4 v[144:145], v[88:91], off
	global_store_dwordx4 v[146:147], v[80:83], off
	global_store_dwordx4 v[150:151], v[72:75], off
	v_cvt_pk_bf16_f32 v65, v70, v71
	v_cvt_pk_bf16_f32 v66, v66, v67
	v_cvt_pk_bf16_f32 v67, v76, v77
	global_store_dwordx4 v[128:129], v[64:67], off
	global_load_dwordx4 v[68:71], v[216:217], off offset:528
	global_load_dwordx4 v[84:87], v[216:217], off offset:512
	global_load_dwordx4 v[76:79], v[214:215], off offset:528
	global_load_dwordx4 v[92:95], v[214:215], off offset:512
	global_load_dwordx4 v[130:133], v[218:219], off offset:256
	global_load_dwordx4 v[134:137], v[224:225], off offset:256
	global_load_dwordx4 v[138:141], v[228:229], off offset:256
	global_load_dwordx4 v[210:213], v[230:231], off offset:256
	s_waitcnt vmcnt(0)
	v_lshlrev_b32_e32 v125, 16, v130
	v_and_b32_e32 v127, 0xffff0000, v130
	v_lshlrev_b32_e32 v130, 16, v131
	v_and_b32_e32 v131, 0xffff0000, v131
	v_lshlrev_b32_e32 v142, 16, v132
	v_and_b32_e32 v143, 0xffff0000, v132
	v_lshlrev_b32_e32 v153, 16, v133
	v_and_b32_e32 v155, 0xffff0000, v133
	v_sub_f32_e32 v131, v131, v208
	v_sub_f32_e32 v130, v130, v208
	v_sub_f32_e32 v133, v127, v208
	v_sub_f32_e32 v132, v125, v208
	v_pk_mul_f32 v[132:133], v[206:207], v[132:133] op_sel_hi:[0,1]
	v_pk_mul_f32 v[130:131], v[206:207], v[130:131] op_sel_hi:[0,1]
	v_pk_fma_f32 v[130:131], v[86:87], v[130:131], v[94:95]
	v_pk_fma_f32 v[132:133], v[84:85], v[132:133], v[92:93]
	v_pk_mul_f32 v[130:131], v[176:177], v[130:131] op_sel_hi:[0,1]
	v_pk_mul_f32 v[132:133], v[176:177], v[132:133] op_sel_hi:[0,1]
	v_pk_fma_f32 v[62:63], v[62:63], v[174:175], v[130:131] op_sel_hi:[1,0,1]
	v_pk_fma_f32 v[60:61], v[60:61], v[174:175], v[132:133] op_sel_hi:[1,0,1]
	v_sub_f32_e32 v131, v155, v208
	v_sub_f32_e32 v130, v153, v208
	v_sub_f32_e32 v133, v143, v208
	v_sub_f32_e32 v132, v142, v208
	v_pk_mul_f32 v[132:133], v[206:207], v[132:133] op_sel_hi:[0,1]
	v_pk_mul_f32 v[130:131], v[206:207], v[130:131] op_sel_hi:[0,1]
	v_pk_fma_f32 v[130:131], v[70:71], v[130:131], v[78:79]
	v_pk_fma_f32 v[132:133], v[68:69], v[132:133], v[76:77]
	v_pk_mul_f32 v[130:131], v[176:177], v[130:131] op_sel_hi:[0,1]
	v_pk_mul_f32 v[132:133], v[176:177], v[132:133] op_sel_hi:[0,1]
	v_pk_fma_f32 v[130:131], v[58:59], v[174:175], v[130:131] op_sel_hi:[1,0,1]
	v_pk_fma_f32 v[58:59], v[56:57], v[174:175], v[132:133] op_sel_hi:[1,0,1]
	v_cvt_pk_bf16_f32 v57, v62, v63
	v_cvt_pk_bf16_f32 v56, v60, v61
	v_and_b32_e32 v125, 0xffff0000, v134
	v_cvt_pk_bf16_f32 v58, v58, v59
	v_cvt_pk_bf16_f32 v59, v130, v131
	global_store_dwordx4 v[232:233], v[56:59], off offset:256
	v_and_b32_e32 v63, 0xffff0000, v59
	v_and_b32_e32 v62, 0xffff0000, v58
	v_lshlrev_b32_e32 v61, 16, v59
	v_lshlrev_b32_e32 v60, 16, v58
	v_pk_mul_f32 v[58:59], v[62:63], v[62:63]
	v_lshlrev_b32_e32 v127, 16, v135
	v_pk_fma_f32 v[58:59], v[60:61], v[60:61], v[58:59]
	v_and_b32_e32 v130, 0xffff0000, v135
	v_pk_add_f32 v[58:59], v[58:59], v[58:59] op_sel_hi:[0,1]
	v_lshlrev_b32_e32 v58, 16, v134
	v_sub_f32_e32 v131, v130, v204
	v_sub_f32_e32 v130, v127, v204
	v_sub_f32_e32 v133, v125, v204
	v_sub_f32_e32 v132, v58, v204
	v_pk_mul_f32 v[132:133], v[202:203], v[132:133] op_sel_hi:[0,1]
	v_pk_mul_f32 v[130:131], v[202:203], v[130:131] op_sel_hi:[0,1]
	v_pk_fma_f32 v[130:131], v[86:87], v[130:131], v[94:95]
	v_pk_fma_f32 v[132:133], v[84:85], v[132:133], v[92:93]
	v_lshlrev_b32_e32 v134, 16, v136
	v_and_b32_e32 v135, 0xffff0000, v136
	v_lshlrev_b32_e32 v136, 16, v137
	v_and_b32_e32 v137, 0xffff0000, v137
	v_pk_mul_f32 v[132:133], v[176:177], v[132:133] op_sel_hi:[0,1]
	v_pk_mul_f32 v[130:131], v[176:177], v[130:131] op_sel_hi:[0,1]
	v_pk_fma_f32 v[54:55], v[54:55], v[174:175], v[130:131] op_sel_hi:[1,0,1]
	v_pk_fma_f32 v[52:53], v[52:53], v[174:175], v[132:133] op_sel_hi:[1,0,1]
	v_sub_f32_e32 v131, v137, v204
	v_sub_f32_e32 v130, v136, v204
	v_sub_f32_e32 v133, v135, v204
	v_sub_f32_e32 v132, v134, v204
	v_pk_mul_f32 v[132:133], v[202:203], v[132:133] op_sel_hi:[0,1]
	v_pk_mul_f32 v[130:131], v[202:203], v[130:131] op_sel_hi:[0,1]
	v_pk_fma_f32 v[130:131], v[70:71], v[130:131], v[78:79]
	v_pk_fma_f32 v[132:133], v[68:69], v[132:133], v[76:77]
	v_pk_mul_f32 v[130:131], v[176:177], v[130:131] op_sel_hi:[0,1]
; __device__ __forceinline__ unsigned cvt_pk_bf16(float lo, float hi) { unsigned r; asm("v_cvt_pk_bf16_f32 %0, %1, %2" : "=v"(r) : "v"(lo), "v"(hi)); return r; }
; __device__ __forceinline__ float bf_lo(unsigned w) { return __uint_as_float(w << 16); }
; __device__ __forceinline__ float bf_hi(unsigned w) { return __uint_as_float(w & 0xffff0000u); }
;     __device__ __forceinline__ void operator()(const f32x4 (&acc)[2][2][4][2], const Unit& u, int wr, int wc, int fr_in, int fq_in) const {
;     ...
;             for (int ai = 0; ai < 2; ++ai) {
;                 f32x4 pf[4][2]; u32x4 pb[4];
; #pragma unroll
;                 for (int m = 0; m < 4; ++m) { const size_t off = (size_t)(row0 + ai * HALF + m * 16) * 1024 + col0 + bj * HALF;
;                     if constexpr (BASE == 0) { pf[m][0] = *(const f32x4*)(basef + off); pf[m][1] = *(const f32x4*)(basef + off + 4); } else pb[m] = *(const u32x4*)(baseb + off); }
; #pragma unroll
;                 for (int m = 0; m < 4; ++m) { const size_t off = (size_t)(row0 + ai * HALF + m * 16) * 1024 + col0 + bj * HALF; f32x4 b[2];
;                     if constexpr (BASE == 0) { b[0] = pf[m][0]; b[1] = pf[m][1]; }
;                     else { const u32x4 pw = pb[m]; b[0] = (f32x4){bf_lo(pw.x), bf_hi(pw.x), bf_lo(pw.y), bf_hi(pw.y)}; b[1] = (f32x4){bf_lo(pw.z), bf_hi(pw.z), bf_lo(pw.w), bf_hi(pw.w)}; }
;                     f32x4 z[2];
; #pragma unroll
;                     for (int n = 0; n < 2; ++n) { if constexpr (BASE == 1) b[n] = (b[n] - rst.mu[ai][m]) * rst.rs[ai][m] * gv[n] + bv[n];
;                         z[n] = b[n] * al_ + acc[ai][bj][m][n] * s_; }
;                     u32x4 w; w.x = cvt_pk_bf16(z[0][0], z[0][1]); w.y = cvt_pk_bf16(z[0][2], z[0][3]); w.z = cvt_pk_bf16(z[1][0], z[1][1]); w.w = cvt_pk_bf16(z[1][2], z[1][3]);
;                     *(u32x4*)(zb + off) = w;
;                     const float r0 = bf_lo(w.x), r1 = bf_hi(w.x), r2 = bf_lo(w.y), r3 = bf_hi(w.y), r4 = bf_lo(w.z), r5 = bf_hi(w.z), r6 = bf_lo(w.w), r7 = bf_hi(w.w);
;                     s1[ai][m] += ((r0 + r1) + (r2 + r3)) + ((r4 + r5) + (r6 + r7)); s2[ai][m] += ((r0 * r0 + r1 * r1) + (r2 * r2 + r3 * r3)) + ((r4 * r4 + r5 * r5) + (r6 * r6 + r7 * r7)); }
	v_pk_mul_f32 v[132:133], v[176:177], v[132:133] op_sel_hi:[0,1]
	v_pk_fma_f32 v[130:131], v[50:51], v[174:175], v[130:131] op_sel_hi:[1,0,1]
	v_pk_fma_f32 v[50:51], v[48:49], v[174:175], v[132:133] op_sel_hi:[1,0,1]
	v_cvt_pk_bf16_f32 v48, v52, v53
	v_cvt_pk_bf16_f32 v49, v54, v55
	v_lshlrev_b32_e32 v54, 16, v138
	v_and_b32_e32 v55, 0xffff0000, v138
	v_lshlrev_b32_e32 v52, 16, v139
	v_and_b32_e32 v53, 0xffff0000, v139
	v_sub_f32_e32 v53, v53, v200
	v_sub_f32_e32 v52, v52, v200
	v_sub_f32_e32 v55, v55, v200
	v_sub_f32_e32 v54, v54, v200
	v_pk_mul_f32 v[54:55], v[198:199], v[54:55] op_sel_hi:[0,1]
	v_pk_mul_f32 v[52:53], v[198:199], v[52:53] op_sel_hi:[0,1]
	v_pk_fma_f32 v[52:53], v[86:87], v[52:53], v[94:95]
	v_pk_fma_f32 v[54:55], v[84:85], v[54:55], v[92:93]
	v_cvt_pk_bf16_f32 v50, v50, v51
	v_cvt_pk_bf16_f32 v51, v130, v131
	global_store_dwordx4 v[116:117], v[48:51], off offset:256
	v_lshlrev_b32_e32 v58, 16, v140
	v_and_b32_e32 v116, 0xffff0000, v140
	v_lshlrev_b32_e32 v117, 16, v141
	v_and_b32_e32 v125, 0xffff0000, v141
	v_pk_mul_f32 v[54:55], v[176:177], v[54:55] op_sel_hi:[0,1]
	v_pk_mul_f32 v[52:53], v[176:177], v[52:53] op_sel_hi:[0,1]
	v_pk_fma_f32 v[46:47], v[46:47], v[174:175], v[52:53] op_sel_hi:[1,0,1]
	v_pk_fma_f32 v[44:45], v[44:45], v[174:175], v[54:55] op_sel_hi:[1,0,1]
	v_sub_f32_e32 v53, v125, v200
	v_sub_f32_e32 v52, v117, v200
	v_sub_f32_e32 v55, v116, v200
	v_sub_f32_e32 v54, v58, v200
	v_pk_mul_f32 v[54:55], v[198:199], v[54:55] op_sel_hi:[0,1]
	v_pk_mul_f32 v[52:53], v[198:199], v[52:53] op_sel_hi:[0,1]
	v_pk_fma_f32 v[52:53], v[70:71], v[52:53], v[78:79]
	v_pk_fma_f32 v[54:55], v[68:69], v[54:55], v[76:77]
	v_pk_mul_f32 v[52:53], v[176:177], v[52:53] op_sel_hi:[0,1]
	v_pk_mul_f32 v[54:55], v[176:177], v[54:55] op_sel_hi:[0,1]
	v_pk_fma_f32 v[52:53], v[42:43], v[174:175], v[52:53] op_sel_hi:[1,0,1]
	v_pk_fma_f32 v[42:43], v[40:41], v[174:175], v[54:55] op_sel_hi:[1,0,1]
	v_cvt_pk_bf16_f32 v40, v44, v45
	v_cvt_pk_bf16_f32 v41, v46, v47
	v_lshlrev_b32_e32 v46, 16, v210
	v_and_b32_e32 v47, 0xffff0000, v210
	v_lshlrev_b32_e32 v44, 16, v211
	v_and_b32_e32 v45, 0xffff0000, v211
	v_sub_f32_e32 v45, v45, v196
	v_sub_f32_e32 v44, v44, v196
	v_sub_f32_e32 v47, v47, v196
	v_sub_f32_e32 v46, v46, v196
	v_pk_mul_f32 v[46:47], v[194:195], v[46:47] op_sel_hi:[0,1]
	v_pk_mul_f32 v[44:45], v[194:195], v[44:45] op_sel_hi:[0,1]
	v_pk_fma_f32 v[44:45], v[86:87], v[44:45], v[94:95]
	v_pk_fma_f32 v[46:47], v[84:85], v[46:47], v[92:93]
	v_cvt_pk_bf16_f32 v42, v42, v43
	v_cvt_pk_bf16_f32 v43, v52, v53
	v_lshlrev_b32_e32 v52, 16, v212
	v_and_b32_e32 v53, 0xffff0000, v212
	v_lshlrev_b32_e32 v54, 16, v213
	v_and_b32_e32 v55, 0xffff0000, v213
	v_pk_mul_f32 v[46:47], v[176:177], v[46:47] op_sel_hi:[0,1]
	v_pk_mul_f32 v[44:45], v[176:177], v[44:45] op_sel_hi:[0,1]
	v_pk_fma_f32 v[38:39], v[38:39], v[174:175], v[44:45] op_sel_hi:[1,0,1]
	v_pk_fma_f32 v[36:37], v[36:37], v[174:175], v[46:47] op_sel_hi:[1,0,1]
	v_sub_f32_e32 v45, v55, v196
	v_sub_f32_e32 v44, v54, v196
	v_sub_f32_e32 v47, v53, v196
	v_sub_f32_e32 v46, v52, v196
	v_pk_mul_f32 v[46:47], v[194:195], v[46:47] op_sel_hi:[0,1]
	v_pk_mul_f32 v[44:45], v[194:195], v[44:45] op_sel_hi:[0,1]
	v_pk_fma_f32 v[44:45], v[70:71], v[44:45], v[78:79]
	v_pk_fma_f32 v[46:47], v[68:69], v[46:47], v[76:77]
	v_pk_mul_f32 v[44:45], v[176:177], v[44:45] op_sel_hi:[0,1]
	v_pk_mul_f32 v[46:47], v[176:177], v[46:47] op_sel_hi:[0,1]
	v_pk_fma_f32 v[44:45], v[34:35], v[174:175], v[44:45] op_sel_hi:[1,0,1]
	v_pk_fma_f32 v[34:35], v[32:33], v[174:175], v[46:47] op_sel_hi:[1,0,1]
	global_store_dwordx4 v[108:109], v[40:43], off offset:256
	v_cvt_pk_bf16_f32 v32, v36, v37
	v_cvt_pk_bf16_f32 v33, v38, v39
	v_cvt_pk_bf16_f32 v34, v34, v35
	v_cvt_pk_bf16_f32 v35, v44, v45
	global_store_dwordx4 v[100:101], v[32:35], off offset:256
	global_load_dwordx4 v[36:39], v[102:103], off offset:256
	global_load_dwordx4 v[44:47], v[110:111], off offset:256
	global_load_dwordx4 v[52:55], v[148:149], off offset:256
	s_nop 0
	global_load_dwordx4 v[100:103], v[118:119], off offset:256
	v_mov_b32_e32 v165, v59
	s_waitcnt vmcnt(0)
	v_lshlrev_b32_e32 v58, 16, v36
	v_and_b32_e32 v108, 0xffff0000, v36
	v_lshlrev_b32_e32 v36, 16, v37
	v_and_b32_e32 v37, 0xffff0000, v37
	v_lshlrev_b32_e32 v109, 16, v38
	v_and_b32_e32 v110, 0xffff0000, v38
	v_lshlrev_b32_e32 v111, 16, v39
	v_and_b32_e32 v116, 0xffff0000, v39
	v_sub_f32_e32 v37, v37, v192
	v_sub_f32_e32 v36, v36, v192
	v_sub_f32_e32 v39, v108, v192
	v_sub_f32_e32 v38, v58, v192
	v_pk_mul_f32 v[38:39], v[190:191], v[38:39] op_sel_hi:[0,1]
	v_pk_mul_f32 v[36:37], v[190:191], v[36:37] op_sel_hi:[0,1]
	v_pk_fma_f32 v[36:37], v[86:87], v[36:37], v[94:95]
	v_pk_fma_f32 v[38:39], v[84:85], v[38:39], v[92:93]
	v_pk_mul_f32 v[36:37], v[176:177], v[36:37] op_sel_hi:[0,1]
	v_pk_mul_f32 v[38:39], v[176:177], v[38:39] op_sel_hi:[0,1]
	v_pk_fma_f32 v[30:31], v[30:31], v[174:175], v[36:37] op_sel_hi:[1,0,1]
	v_pk_fma_f32 v[28:29], v[28:29], v[174:175], v[38:39] op_sel_hi:[1,0,1]
	v_sub_f32_e32 v37, v116, v192
	v_sub_f32_e32 v36, v111, v192
	v_sub_f32_e32 v39, v110, v192
	v_sub_f32_e32 v38, v109, v192
	v_pk_mul_f32 v[38:39], v[190:191], v[38:39] op_sel_hi:[0,1]
	v_pk_mul_f32 v[36:37], v[190:191], v[36:37] op_sel_hi:[0,1]
	v_pk_fma_f32 v[36:37], v[70:71], v[36:37], v[78:79]
	v_pk_fma_f32 v[38:39], v[68:69], v[38:39], v[76:77]
	v_pk_mul_f32 v[36:37], v[176:177], v[36:37] op_sel_hi:[0,1]
	v_pk_mul_f32 v[38:39], v[176:177], v[38:39] op_sel_hi:[0,1]
	v_pk_fma_f32 v[36:37], v[26:27], v[174:175], v[36:37] op_sel_hi:[1,0,1]
	v_pk_fma_f32 v[26:27], v[24:25], v[174:175], v[38:39] op_sel_hi:[1,0,1]
; __device__ __forceinline__ unsigned cvt_pk_bf16(float lo, float hi) { unsigned r; asm("v_cvt_pk_bf16_f32 %0, %1, %2" : "=v"(r) : "v"(lo), "v"(hi)); return r; }
; __device__ __forceinline__ float bf_lo(unsigned w) { return __uint_as_float(w << 16); }
; __device__ __forceinline__ float bf_hi(unsigned w) { return __uint_as_float(w & 0xffff0000u); }
;     __device__ __forceinline__ void operator()(const f32x4 (&acc)[2][2][4][2], const Unit& u, int wr, int wc, int fr_in, int fq_in) const {
;     ...
;             for (int ai = 0; ai < 2; ++ai) {
;                 f32x4 pf[4][2]; u32x4 pb[4];
; #pragma unroll
;                 for (int m = 0; m < 4; ++m) { const size_t off = (size_t)(row0 + ai * HALF + m * 16) * 1024 + col0 + bj * HALF;
;                     if constexpr (BASE == 0) { pf[m][0] = *(const f32x4*)(basef + off); pf[m][1] = *(const f32x4*)(basef + off + 4); } else pb[m] = *(const u32x4*)(baseb + off); }
; #pragma unroll
;                 for (int m = 0; m < 4; ++m) { const size_t off = (size_t)(row0 + ai * HALF + m * 16) * 1024 + col0 + bj * HALF; f32x4 b[2];
;                     if constexpr (BASE == 0) { b[0] = pf[m][0]; b[1] = pf[m][1]; }
;                     else { const u32x4 pw = pb[m]; b[0] = (f32x4){bf_lo(pw.x), bf_hi(pw.x), bf_lo(pw.y), bf_hi(pw.y)}; b[1] = (f32x4){bf_lo(pw.z), bf_hi(pw.z), bf_lo(pw.w), bf_hi(pw.w)}; }
;                     f32x4 z[2];
; #pragma unroll
;                     for (int n = 0; n < 2; ++n) { if constexpr (BASE == 1) b[n] = (b[n] - rst.mu[ai][m]) * rst.rs[ai][m] * gv[n] + bv[n];
;                         z[n] = b[n] * al_ + acc[ai][bj][m][n] * s_; }
;                     u32x4 w; w.x = cvt_pk_bf16(z[0][0], z[0][1]); w.y = cvt_pk_bf16(z[0][2], z[0][3]); w.z = cvt_pk_bf16(z[1][0], z[1][1]); w.w = cvt_pk_bf16(z[1][2], z[1][3]);
;                     *(u32x4*)(zb + off) = w;
;                     const float r0 = bf_lo(w.x), r1 = bf_hi(w.x), r2 = bf_lo(w.y), r3 = bf_hi(w.y), r4 = bf_lo(w.z), r5 = bf_hi(w.z), r6 = bf_lo(w.w), r7 = bf_hi(w.w);
;                     s1[ai][m] += ((r0 + r1) + (r2 + r3)) + ((r4 + r5) + (r6 + r7)); s2[ai][m] += ((r0 * r0 + r1 * r1) + (r2 * r2 + r3 * r3)) + ((r4 * r4 + r5 * r5) + (r6 * r6 + r7 * r7)); }
	v_cvt_pk_bf16_f32 v24, v28, v29
	v_cvt_pk_bf16_f32 v25, v30, v31
	v_lshlrev_b32_e32 v30, 16, v44
	v_and_b32_e32 v31, 0xffff0000, v44
	v_lshlrev_b32_e32 v28, 16, v45
	v_and_b32_e32 v29, 0xffff0000, v45
	v_sub_f32_e32 v29, v29, v188
	v_sub_f32_e32 v28, v28, v188
	v_sub_f32_e32 v31, v31, v188
	v_sub_f32_e32 v30, v30, v188
	v_pk_mul_f32 v[30:31], v[186:187], v[30:31] op_sel_hi:[0,1]
	v_pk_mul_f32 v[28:29], v[186:187], v[28:29] op_sel_hi:[0,1]
	v_pk_fma_f32 v[28:29], v[86:87], v[28:29], v[94:95]
	v_pk_fma_f32 v[30:31], v[84:85], v[30:31], v[92:93]
	v_cvt_pk_bf16_f32 v26, v26, v27
	v_cvt_pk_bf16_f32 v27, v36, v37
	v_lshlrev_b32_e32 v36, 16, v46
	v_and_b32_e32 v37, 0xffff0000, v46
	v_lshlrev_b32_e32 v38, 16, v47
	v_and_b32_e32 v39, 0xffff0000, v47
	v_pk_mul_f32 v[30:31], v[176:177], v[30:31] op_sel_hi:[0,1]
	v_pk_mul_f32 v[28:29], v[176:177], v[28:29] op_sel_hi:[0,1]
	v_pk_fma_f32 v[22:23], v[22:23], v[174:175], v[28:29] op_sel_hi:[1,0,1]
	v_pk_fma_f32 v[20:21], v[20:21], v[174:175], v[30:31] op_sel_hi:[1,0,1]
	v_sub_f32_e32 v29, v39, v188
	v_sub_f32_e32 v28, v38, v188
	v_sub_f32_e32 v31, v37, v188
	v_sub_f32_e32 v30, v36, v188
	v_pk_mul_f32 v[30:31], v[186:187], v[30:31] op_sel_hi:[0,1]
	v_pk_mul_f32 v[28:29], v[186:187], v[28:29] op_sel_hi:[0,1]
	v_pk_fma_f32 v[28:29], v[70:71], v[28:29], v[78:79]
	v_pk_fma_f32 v[30:31], v[68:69], v[30:31], v[76:77]
	v_pk_mul_f32 v[28:29], v[176:177], v[28:29] op_sel_hi:[0,1]
	v_pk_mul_f32 v[30:31], v[176:177], v[30:31] op_sel_hi:[0,1]
	v_pk_fma_f32 v[28:29], v[18:19], v[174:175], v[28:29] op_sel_hi:[1,0,1]
	v_pk_fma_f32 v[18:19], v[16:17], v[174:175], v[30:31] op_sel_hi:[1,0,1]
	v_cvt_pk_bf16_f32 v16, v20, v21
	v_cvt_pk_bf16_f32 v17, v22, v23
	v_lshlrev_b32_e32 v22, 16, v52
	v_and_b32_e32 v23, 0xffff0000, v52
	v_lshlrev_b32_e32 v20, 16, v53
	v_and_b32_e32 v21, 0xffff0000, v53
	v_sub_f32_e32 v21, v21, v184
	v_sub_f32_e32 v20, v20, v184
	v_sub_f32_e32 v23, v23, v184
	v_sub_f32_e32 v22, v22, v184
	v_pk_mul_f32 v[22:23], v[182:183], v[22:23] op_sel_hi:[0,1]
	v_pk_mul_f32 v[20:21], v[182:183], v[20:21] op_sel_hi:[0,1]
	v_pk_fma_f32 v[20:21], v[86:87], v[20:21], v[94:95]
	v_pk_fma_f32 v[22:23], v[84:85], v[22:23], v[92:93]
	v_cvt_pk_bf16_f32 v18, v18, v19
	v_cvt_pk_bf16_f32 v19, v28, v29
	v_lshlrev_b32_e32 v28, 16, v54
	v_and_b32_e32 v29, 0xffff0000, v54
	v_lshlrev_b32_e32 v30, 16, v55
	v_and_b32_e32 v31, 0xffff0000, v55
	v_pk_mul_f32 v[22:23], v[176:177], v[22:23] op_sel_hi:[0,1]
	v_pk_mul_f32 v[20:21], v[176:177], v[20:21] op_sel_hi:[0,1]
	v_pk_fma_f32 v[14:15], v[14:15], v[174:175], v[20:21] op_sel_hi:[1,0,1]
	v_pk_fma_f32 v[12:13], v[12:13], v[174:175], v[22:23] op_sel_hi:[1,0,1]
	v_sub_f32_e32 v21, v31, v184
	v_sub_f32_e32 v20, v30, v184
	v_sub_f32_e32 v23, v29, v184
	v_sub_f32_e32 v22, v28, v184
	v_pk_mul_f32 v[22:23], v[182:183], v[22:23] op_sel_hi:[0,1]
	v_pk_mul_f32 v[20:21], v[182:183], v[20:21] op_sel_hi:[0,1]
	v_pk_fma_f32 v[20:21], v[70:71], v[20:21], v[78:79]
	v_pk_fma_f32 v[22:23], v[68:69], v[22:23], v[76:77]
	v_pk_mul_f32 v[20:21], v[176:177], v[20:21] op_sel_hi:[0,1]
	v_pk_mul_f32 v[22:23], v[176:177], v[22:23] op_sel_hi:[0,1]
	v_pk_fma_f32 v[20:21], v[10:11], v[174:175], v[20:21] op_sel_hi:[1,0,1]
	v_pk_fma_f32 v[10:11], v[8:9], v[174:175], v[22:23] op_sel_hi:[1,0,1]
	v_cvt_pk_bf16_f32 v8, v12, v13
	v_cvt_pk_bf16_f32 v9, v14, v15
	v_lshlrev_b32_e32 v14, 16, v100
	v_and_b32_e32 v15, 0xffff0000, v100
	v_lshlrev_b32_e32 v12, 16, v101
	v_and_b32_e32 v13, 0xffff0000, v101
	v_sub_f32_e32 v13, v13, v180
	v_sub_f32_e32 v12, v12, v180
	v_sub_f32_e32 v15, v15, v180
	v_sub_f32_e32 v14, v14, v180
	v_pk_mul_f32 v[14:15], v[178:179], v[14:15] op_sel_hi:[0,1]
	v_pk_mul_f32 v[12:13], v[178:179], v[12:13] op_sel_hi:[0,1]
	v_pk_fma_f32 v[12:13], v[86:87], v[12:13], v[94:95]
	v_pk_fma_f32 v[14:15], v[84:85], v[14:15], v[92:93]
	v_cvt_pk_bf16_f32 v10, v10, v11
	v_cvt_pk_bf16_f32 v11, v20, v21
	v_lshlrev_b32_e32 v20, 16, v102
; __device__ __forceinline__ unsigned cvt_pk_bf16(float lo, float hi) { unsigned r; asm("v_cvt_pk_bf16_f32 %0, %1, %2" : "=v"(r) : "v"(lo), "v"(hi)); return r; }
; __device__ __forceinline__ float bf_lo(unsigned w) { return __uint_as_float(w << 16); }
; __device__ __forceinline__ float bf_hi(unsigned w) { return __uint_as_float(w & 0xffff0000u); }
; __device__ __forceinline__ void emit_row_stats(float (&s1)[2][4], float (&s2)[2][4], float* sp_new, const Unit& u, int wr, int wc, int fr, int fq, PG8_LAS unsigned char* xl) {
;     ...
;         for (int m = 0; m < 4; ++m) { float a = s1[ai][m], b = s2[ai][m]; a += __shfl_xor(a, 16); b += __shfl_xor(b, 16); a += __shfl_xor(a, 32); b += __shfl_xor(b, 32);
;             if (fq == 0) P[(ai * HALF + wr * 64 + m * 16 + fr) * 4 + wc] = (f32x2v){a, b}; }
;     __device__ __forceinline__ void operator()(const f32x4 (&acc)[2][2][4][2], const Unit& u, int wr, int wc, int fr_in, int fq_in) const {
;     ...
;                 for (int m = 0; m < 4; ++m) { const size_t off = (size_t)(row0 + ai * HALF + m * 16) * 1024 + col0 + bj * HALF; f32x4 b[2];
;                     if constexpr (BASE == 0) { b[0] = pf[m][0]; b[1] = pf[m][1]; }
;                     else { const u32x4 pw = pb[m]; b[0] = (f32x4){bf_lo(pw.x), bf_hi(pw.x), bf_lo(pw.y), bf_hi(pw.y)}; b[1] = (f32x4){bf_lo(pw.z), bf_hi(pw.z), bf_lo(pw.w), bf_hi(pw.w)}; }
;                     f32x4 z[2];
; #pragma unroll
;                     for (int n = 0; n < 2; ++n) { if constexpr (BASE == 1) b[n] = (b[n] - rst.mu[ai][m]) * rst.rs[ai][m] * gv[n] + bv[n];
;                         z[n] = b[n] * al_ + acc[ai][bj][m][n] * s_; }
;                     u32x4 w; w.x = cvt_pk_bf16(z[0][0], z[0][1]); w.y = cvt_pk_bf16(z[0][2], z[0][3]); w.z = cvt_pk_bf16(z[1][0], z[1][1]); w.w = cvt_pk_bf16(z[1][2], z[1][3]);
;                     *(u32x4*)(zb + off) = w;
;                     const float r0 = bf_lo(w.x), r1 = bf_hi(w.x), r2 = bf_lo(w.y), r3 = bf_hi(w.y), r4 = bf_lo(w.z), r5 = bf_hi(w.z), r6 = bf_lo(w.w), r7 = bf_hi(w.w);
;                     s1[ai][m] += ((r0 + r1) + (r2 + r3)) + ((r4 + r5) + (r6 + r7)); s2[ai][m] += ((r0 * r0 + r1 * r1) + (r2 * r2 + r3 * r3)) + ((r4 * r4 + r5 * r5) + (r6 * r6 + r7 * r7)); }
	v_and_b32_e32 v21, 0xffff0000, v102
	v_lshlrev_b32_e32 v22, 16, v103
	v_and_b32_e32 v23, 0xffff0000, v103
	v_pk_mul_f32 v[14:15], v[176:177], v[14:15] op_sel_hi:[0,1]
	v_pk_mul_f32 v[12:13], v[176:177], v[12:13] op_sel_hi:[0,1]
	v_pk_fma_f32 v[6:7], v[6:7], v[174:175], v[12:13] op_sel_hi:[1,0,1]
	v_pk_fma_f32 v[4:5], v[4:5], v[174:175], v[14:15] op_sel_hi:[1,0,1]
	v_sub_f32_e32 v13, v23, v180
	v_sub_f32_e32 v12, v22, v180
	v_sub_f32_e32 v15, v21, v180
	v_sub_f32_e32 v14, v20, v180
	v_pk_mul_f32 v[14:15], v[178:179], v[14:15] op_sel_hi:[0,1]
	v_pk_mul_f32 v[12:13], v[178:179], v[12:13] op_sel_hi:[0,1]
	v_pk_fma_f32 v[12:13], v[70:71], v[12:13], v[78:79]
	v_pk_fma_f32 v[14:15], v[68:69], v[14:15], v[76:77]
	v_pk_mul_f32 v[12:13], v[176:177], v[12:13] op_sel_hi:[0,1]
	v_pk_mul_f32 v[14:15], v[176:177], v[14:15] op_sel_hi:[0,1]
	v_pk_fma_f32 v[12:13], v[2:3], v[174:175], v[12:13] op_sel_hi:[1,0,1]
	v_pk_fma_f32 v[2:3], v[0:1], v[174:175], v[14:15] op_sel_hi:[1,0,1]
	v_cvt_pk_bf16_f32 v0, v4, v5
	v_and_b32_e32 v5, 64, v195
	v_xor_b32_e32 v4, 16, v195
	v_add_u32_e32 v5, 64, v5
	v_cmp_lt_i32_e32 vcc, v4, v5
	v_cvt_pk_bf16_f32 v2, v2, v3
	v_cvt_pk_bf16_f32 v3, v12, v13
	v_cvt_pk_bf16_f32 v1, v6, v7
	v_and_b32_e32 v21, 0xffff0000, v56
	v_and_b32_e32 v20, 0xffff0000, v121
	v_cndmask_b32_e32 v4, v195, v4, vcc
	v_lshlrev_b32_e32 v13, 2, v4
	v_xor_b32_e32 v4, 32, v195
	v_cmp_lt_i32_e32 vcc, v4, v5
	v_lshlrev_b32_e32 v5, 16, v56
	v_mov_b32_e32 v155, v5
	v_cndmask_b32_e32 v4, v195, v4, vcc
	v_lshlrev_b32_e32 v12, 2, v4
	v_lshlrev_b32_e32 v4, 16, v120
	v_pk_mul_f32 v[6:7], v[4:5], v[4:5]
	v_pk_mul_f32 v[14:15], v[154:155], v[154:155]
	v_mov_b32_e32 v153, v21
	v_pk_mov_b32 v[54:55], v[4:5], v[6:7] op_sel:[1,0]
	v_pk_add_f32 v[4:5], v[4:5], v[154:155]
	v_pk_mul_f32 v[22:23], v[152:153], v[152:153]
	v_pk_mul_f32 v[28:29], v[20:21], v[20:21]
	v_lshlrev_b32_e32 v30, 16, v122
	v_lshlrev_b32_e32 v31, 16, v57
	v_and_b32_e32 v45, 0xffff0000, v57
	v_and_b32_e32 v44, 0xffff0000, v123
	v_pk_mov_b32 v[14:15], v[20:21], v[14:15] op_sel:[1,0]
	v_mov_b32_e32 v5, v7
	v_pk_add_f32 v[6:7], v[20:21], v[152:153]
	v_mov_b32_e32 v127, v31
	v_mov_b32_e32 v125, v45
	v_pk_add_f32 v[14:15], v[54:55], v[14:15]
	v_pk_mov_b32 v[22:23], v[30:31], v[22:23] op_sel:[1,0]
	v_pk_mov_b32 v[54:55], v[44:45], v[28:29] op_sel:[1,0]
	v_mov_b32_e32 v7, v29
	v_pk_mul_f32 v[36:37], v[30:31], v[30:31]
	v_pk_mul_f32 v[38:39], v[126:127], v[126:127]
	v_pk_mul_f32 v[46:47], v[124:125], v[124:125]
	v_pk_mul_f32 v[52:53], v[44:45], v[44:45]
	v_pk_add_f32 v[22:23], v[22:23], v[54:55]
	v_pk_add_f32 v[4:5], v[4:5], v[6:7]
	v_pk_add_f32 v[6:7], v[30:31], v[126:127]
	v_pk_add_f32 v[20:21], v[44:45], v[124:125]
	v_pk_add_f32 v[14:15], v[14:15], v[22:23]
	v_mov_b32_e32 v22, v60
	v_mov_b32_e32 v23, v36
	v_mov_b32_e32 v54, v62
	v_mov_b32_e32 v55, v38
	v_pk_mov_b32 v[38:39], v[60:61], v[46:47] op_sel:[1,0]
	v_pk_mov_b32 v[46:47], v[62:63], v[52:53] op_sel:[1,0]
	v_mov_b32_e32 v7, v37
	v_mov_b32_e32 v21, v53
	v_pk_add_f32 v[22:23], v[22:23], v[54:55]
	v_pk_add_f32 v[38:39], v[38:39], v[46:47]
	v_pk_add_f32 v[6:7], v[6:7], v[20:21]
	v_pk_add_f32 v[22:23], v[22:23], v[38:39]
	v_pk_add_f32 v[4:5], v[4:5], v[6:7]
	v_pk_add_f32 v[14:15], v[14:15], v[22:23]
	v_pk_add_f32 v[4:5], v[4:5], v[164:165]
	global_store_dwordx4 v[144:145], v[24:27], off offset:256
	v_pk_add_f32 v[4:5], v[14:15], v[4:5]
	ds_bpermute_b32 v6, v13, v4
	ds_bpermute_b32 v7, v13, v5
	global_store_dwordx4 v[146:147], v[16:19], off offset:256
	global_store_dwordx4 v[150:151], v[8:11], off offset:256
	global_store_dwordx4 v[128:129], v[0:3], off offset:256
	s_waitcnt lgkmcnt(0)
	v_pk_add_f32 v[4:5], v[4:5], v[6:7]
	ds_bpermute_b32 v6, v12, v4
	ds_bpermute_b32 v7, v12, v5
	v_cmp_eq_u32_e32 vcc, 0, v203
	v_lshl_add_u32 v14, v199, 5, s66
	s_and_saveexec_b64 s[8:9], vcc
	s_cbranch_execz .LBB0_1177
	s_waitcnt lgkmcnt(0)
	v_pk_add_f32 v[4:5], v[4:5], v[6:7]
	ds_write_b64 v14, v[4:5]

; __device__ __forceinline__ unsigned cvt_pk_bf16(float lo, float hi) { unsigned r; asm("v_cvt_pk_bf16_f32 %0, %1, %2" : "=v"(r) : "v"(lo), "v"(hi)); return r; }
;     __device__ __forceinline__ void operator()(const f32x4 (&acc)[2][2][4][2], const Unit& u, int wr, int wc, int fr_in, int fq_in) const {
;     ...
;         for (int bj = 0; bj < 2; ++bj) { f32x4 gv[2], bv[2];
;             if constexpr (BASE == 1) {
; #pragma unroll
;                 for (int n = 0; n < 2; ++n) { gv[n] = *(const f32x4*)(lg + col0 + bj * HALF + 4 * n); bv[n] = *(const f32x4*)(lb + col0 + bj * HALF + 4 * n); } }
; #pragma unroll
;             for (int ai = 0; ai < 2; ++ai) {
;                 f32x4 pf[4][2]; u32x4 pb[4];
; #pragma unroll
;                 for (int m = 0; m < 4; ++m) { const size_t off = (size_t)(row0 + ai * HALF + m * 16) * 1024 + col0 + bj * HALF;
;                     if constexpr (BASE == 0) { pf[m][0] = *(const f32x4*)(basef + off); pf[m][1] = *(const f32x4*)(basef + off + 4); } else pb[m] = *(const u32x4*)(baseb + off); }
; #pragma unroll
;                 for (int m = 0; m < 4; ++m) { const size_t off = (size_t)(row0 + ai * HALF + m * 16) * 1024 + col0 + bj * HALF; f32x4 b[2];
;                     if constexpr (BASE == 0) { b[0] = pf[m][0]; b[1] = pf[m][1]; }
;                     else { const u32x4 pw = pb[m]; b[0] = (f32x4){bf_lo(pw.x), bf_hi(pw.x), bf_lo(pw.y), bf_hi(pw.y)}; b[1] = (f32x4){bf_lo(pw.z), bf_hi(pw.z), bf_lo(pw.w), bf_hi(pw.w)}; }
;                     f32x4 z[2];
; #pragma unroll
;                     for (int n = 0; n < 2; ++n) { if constexpr (BASE == 1) b[n] = (b[n] - rst.mu[ai][m]) * rst.rs[ai][m] * gv[n] + bv[n];
;                         z[n] = b[n] * al_ + acc[ai][bj][m][n] * s_; }
;                     u32x4 w; w.x = cvt_pk_bf16(z[0][0], z[0][1]); w.y = cvt_pk_bf16(z[0][2], z[0][3]); w.z = cvt_pk_bf16(z[1][0], z[1][1]); w.w = cvt_pk_bf16(z[1][2], z[1][3]);
;                     *(u32x4*)(zb + off) = w;
;                     const float r0 = bf_lo(w.x), r1 = bf_hi(w.x), r2 = bf_lo(w.y), r3 = bf_hi(w.y), r4 = bf_lo(w.z), r5 = bf_hi(w.z), r6 = bf_lo(w.w), r7 = bf_hi(w.w);
;                     s1[ai][m] += ((r0 + r1) + (r2 + r3)) + ((r4 + r5) + (r6 + r7)); s2[ai][m] += ((r0 * r0 + r1 * r1) + (r2 * r2 + r3 * r3)) + ((r4 * r4 + r5 * r5) + (r6 * r6 + r7 * r7)); }
.LBB0_1365:
	s_lshl_b32 s11, s46, 8
	v_mov_b32_e32 v199, v175
	v_mov_b32_e32 v203, v177
	s_add_i32 s8, s11, s60
	v_mov_b32_e32 v176, 0x3fb504f3
	v_add_u32_e32 v146, s8, v199
	v_ashrrev_i32_e32 v147, 31, v146
	v_mov_b32_e32 v174, 0.5
	v_add_u32_e32 v144, 16, v146
	v_ashrrev_i32_e32 v145, 31, v144
	v_add_u32_e32 v148, 32, v146
	v_ashrrev_i32_e32 v149, 31, v148
	v_add_u32_e32 v150, 48, v146
	v_ashrrev_i32_e32 v151, 31, v150
	v_add_u32_e32 v222, 0x80, v146
	v_ashrrev_i32_e32 v223, 31, v222
	v_add_u32_e32 v226, 0x90, v146
	v_ashrrev_i32_e32 v227, 31, v226
	v_add_u32_e32 v210, 0xa0, v146
	v_ashrrev_i32_e32 v211, 31, v210
	v_add_u32_e32 v212, 0xb0, v146
	v_ashrrev_i32_e32 v213, 31, v212
	s_lshl_b32 s8, s10, 8
	s_or_b32 s8, s8, s61
	v_lshl_add_u32 v152, v203, 3, s8
	v_ashrrev_i32_e32 v153, 31, v152
	v_lshlrev_b64 v[220:221], 1, v[152:153]
	v_lshl_add_u64 v[234:235], s[26:27], 0, v[220:221]
	v_lshlrev_b64 v[232:233], 11, v[146:147]
	v_lshl_add_u64 v[218:219], v[234:235], 0, v[232:233]
	v_lshlrev_b64 v[236:237], 11, v[144:145]
	v_lshl_add_u64 v[224:225], v[234:235], 0, v[236:237]
	v_lshlrev_b64 v[240:241], 11, v[148:149]
	v_lshl_add_u64 v[228:229], v[234:235], 0, v[240:241]
	v_lshlrev_b64 v[238:239], 11, v[150:151]
	v_lshl_add_u64 v[230:231], v[234:235], 0, v[238:239]
	v_and_b32_e32 v181, 0xff, v146
	v_lshlrev_b32_e32 v181, 3, v181
	v_add_u32_e32 v181, 0x22400, v181
	v_and_b32_e32 v208, 0xffffff00, v146
	v_lshlrev_b64 v[128:129], 2, v[152:153]
	v_lshl_add_u64 v[216:217], s[4:5], 0, v[128:129]
	v_lshl_add_u64 v[214:215], s[6:7], 0, v[128:129]
	global_load_dwordx4 v[128:131], v[216:217], off offset:16
	global_load_dwordx4 v[136:139], v[216:217], off
	global_load_dwordx4 v[132:135], v[214:215], off offset:16
	global_load_dwordx4 v[140:143], v[214:215], off
	global_load_dwordx4 v[152:155], v[218:219], off
	global_load_dwordx4 v[144:147], v[224:225], off
	global_load_dwordx4 v[242:245], v[228:229], off
	global_load_dwordx4 v[148:151], v[230:231], off
	v_readfirstlane_b32 s98, v254
	s_nop 0
	s_cmpk_lt_u32 s98, 0x100
	s_cbranch_scc0 .Lrs3_skip
	v_add_u32_e32 v208, v208, v254
	v_mov_b32_e32 v209, 0
	v_lshlrev_b64 v[208:209], 5, v[208:209]
	v_lshl_add_u64 v[208:209], s[22:23], 0, v[208:209]
	global_load_dwordx2 v[204:205], v[208:209], off
	global_load_dwordx2 v[200:201], v[208:209], off offset:8
	global_load_dwordx2 v[196:197], v[208:209], off offset:16
	global_load_dwordx2 v[192:193], v[208:209], off offset:24
	s_waitcnt vmcnt(0)
	v_pk_add_f32 v[196:197], v[196:197], v[192:193]
	v_pk_add_f32 v[204:205], v[204:205], v[200:201]
	s_nop 0
	v_pk_add_f32 v[196:197], v[204:205], v[196:197]
	s_nop 0
	v_pk_mul_f32 v[196:197], v[196:197], s[34:35] op_sel_hi:[1,0]
	v_lshlrev_b32_e32 v188, 3, v254
	v_add_u32_e32 v188, 0x22400, v188
	ds_write_b64 v188, v[196:197]
.Lrs3_skip:
	s_waitcnt vmcnt(0) lgkmcnt(0)
	s_barrier
	ds_read_b64 v[208:209], v181
	ds_read_b64 v[204:205], v181 offset:128
	ds_read_b64 v[200:201], v181 offset:256
	ds_read_b64 v[196:197], v181 offset:384
	ds_read_b64 v[192:193], v181 offset:1024
	ds_read_b64 v[188:189], v181 offset:1152
	ds_read_b64 v[184:185], v181 offset:1280
	ds_read_b64 v[180:181], v181 offset:1408
	s_waitcnt lgkmcnt(0)
	v_fma_f32 v209, -v208, v208, v209
	v_max_f32_e32 v209, 0, v209
	v_add_f32_e32 v209, 0x3727c5ac, v209
	v_rsq_f32_e32 v206, v209
	v_fma_f32 v205, -v204, v204, v205
	v_max_f32_e32 v205, 0, v205
	v_add_f32_e32 v205, 0x3727c5ac, v205
	v_rsq_f32_e32 v202, v205
	v_fma_f32 v201, -v200, v200, v201
	v_max_f32_e32 v201, 0, v201
	v_add_f32_e32 v201, 0x3727c5ac, v201
	v_rsq_f32_e32 v198, v201
	v_fma_f32 v197, -v196, v196, v197
	v_max_f32_e32 v197, 0, v197
	v_add_f32_e32 v197, 0x3727c5ac, v197
	v_rsq_f32_e32 v194, v197
	v_fma_f32 v193, -v192, v192, v193
	v_max_f32_e32 v193, 0, v193
	v_add_f32_e32 v193, 0x3727c5ac, v193
	v_rsq_f32_e32 v190, v193
	v_fma_f32 v189, -v188, v188, v189
	v_max_f32_e32 v189, 0, v189
	v_add_f32_e32 v189, 0x3727c5ac, v189
	v_rsq_f32_e32 v186, v189
	v_fma_f32 v185, -v184, v184, v185
	v_max_f32_e32 v185, 0, v185
	v_add_f32_e32 v185, 0x3727c5ac, v185
	v_rsq_f32_e32 v182, v185
	v_fma_f32 v181, -v180, v180, v181
	v_max_f32_e32 v181, 0, v181
	v_add_f32_e32 v181, 0x3727c5ac, v181
	v_rsq_f32_e32 v178, v181
	s_waitcnt vmcnt(0)
	v_lshlrev_b32_e32 v165, 16, v152
	v_and_b32_e32 v181, 0xffff0000, v152
	v_lshlrev_b32_e32 v152, 16, v153
	v_and_b32_e32 v153, 0xffff0000, v153
	v_lshlrev_b32_e32 v185, 16, v154
	v_and_b32_e32 v189, 0xffff0000, v154
	v_lshlrev_b32_e32 v193, 16, v155
	v_and_b32_e32 v197, 0xffff0000, v155
	v_sub_f32_e32 v153, v153, v208
	v_sub_f32_e32 v152, v152, v208
	v_sub_f32_e32 v155, v181, v208
	v_sub_f32_e32 v154, v165, v208
	v_pk_mul_f32 v[154:155], v[206:207], v[154:155] op_sel_hi:[0,1]
	v_pk_mul_f32 v[152:153], v[206:207], v[152:153] op_sel_hi:[0,1]
	v_pk_fma_f32 v[152:153], v[138:139], v[152:153], v[142:143]
	v_pk_fma_f32 v[154:155], v[136:137], v[154:155], v[140:141]
	v_pk_mul_f32 v[152:153], v[176:177], v[152:153] op_sel_hi:[0,1]
	v_pk_mul_f32 v[154:155], v[176:177], v[154:155] op_sel_hi:[0,1]
	v_pk_fma_f32 v[126:127], v[126:127], v[174:175], v[152:153] op_sel_hi:[1,0,1]
	v_pk_fma_f32 v[124:125], v[124:125], v[174:175], v[154:155] op_sel_hi:[1,0,1]
	v_sub_f32_e32 v153, v197, v208
	v_sub_f32_e32 v152, v193, v208
	v_sub_f32_e32 v155, v189, v208
	v_sub_f32_e32 v154, v185, v208
	v_pk_mul_f32 v[154:155], v[206:207], v[154:155] op_sel_hi:[0,1]
	v_pk_mul_f32 v[152:153], v[206:207], v[152:153] op_sel_hi:[0,1]
	v_pk_fma_f32 v[152:153], v[130:131], v[152:153], v[134:135]
	v_pk_fma_f32 v[154:155], v[128:129], v[154:155], v[132:133]
	v_pk_mul_f32 v[152:153], v[176:177], v[152:153] op_sel_hi:[0,1]
; __device__ __forceinline__ unsigned cvt_pk_bf16(float lo, float hi) { unsigned r; asm("v_cvt_pk_bf16_f32 %0, %1, %2" : "=v"(r) : "v"(lo), "v"(hi)); return r; }
; __device__ __forceinline__ float bf_lo(unsigned w) { return __uint_as_float(w << 16); }
; __device__ __forceinline__ float bf_hi(unsigned w) { return __uint_as_float(w & 0xffff0000u); }
;     __device__ __forceinline__ void operator()(const f32x4 (&acc)[2][2][4][2], const Unit& u, int wr, int wc, int fr_in, int fq_in) const {
;     ...
;             for (int ai = 0; ai < 2; ++ai) {
;                 f32x4 pf[4][2]; u32x4 pb[4];
; #pragma unroll
;                 for (int m = 0; m < 4; ++m) { const size_t off = (size_t)(row0 + ai * HALF + m * 16) * 1024 + col0 + bj * HALF;
;                     if constexpr (BASE == 0) { pf[m][0] = *(const f32x4*)(basef + off); pf[m][1] = *(const f32x4*)(basef + off + 4); } else pb[m] = *(const u32x4*)(baseb + off); }
; #pragma unroll
;                 for (int m = 0; m < 4; ++m) { const size_t off = (size_t)(row0 + ai * HALF + m * 16) * 1024 + col0 + bj * HALF; f32x4 b[2];
;                     if constexpr (BASE == 0) { b[0] = pf[m][0]; b[1] = pf[m][1]; }
;                     else { const u32x4 pw = pb[m]; b[0] = (f32x4){bf_lo(pw.x), bf_hi(pw.x), bf_lo(pw.y), bf_hi(pw.y)}; b[1] = (f32x4){bf_lo(pw.z), bf_hi(pw.z), bf_lo(pw.w), bf_hi(pw.w)}; }
;                     f32x4 z[2];
; #pragma unroll
;                     for (int n = 0; n < 2; ++n) { if constexpr (BASE == 1) b[n] = (b[n] - rst.mu[ai][m]) * rst.rs[ai][m] * gv[n] + bv[n];
;                         z[n] = b[n] * al_ + acc[ai][bj][m][n] * s_; }
;                     u32x4 w; w.x = cvt_pk_bf16(z[0][0], z[0][1]); w.y = cvt_pk_bf16(z[0][2], z[0][3]); w.z = cvt_pk_bf16(z[1][0], z[1][1]); w.w = cvt_pk_bf16(z[1][2], z[1][3]);
;                     *(u32x4*)(zb + off) = w;
;                     const float r0 = bf_lo(w.x), r1 = bf_hi(w.x), r2 = bf_lo(w.y), r3 = bf_hi(w.y), r4 = bf_lo(w.z), r5 = bf_hi(w.z), r6 = bf_lo(w.w), r7 = bf_hi(w.w);
;                     s1[ai][m] += ((r0 + r1) + (r2 + r3)) + ((r4 + r5) + (r6 + r7)); s2[ai][m] += ((r0 * r0 + r1 * r1) + (r2 * r2 + r3 * r3)) + ((r4 * r4 + r5 * r5) + (r6 * r6 + r7 * r7)); }
	v_pk_mul_f32 v[154:155], v[176:177], v[154:155] op_sel_hi:[0,1]
	v_pk_fma_f32 v[152:153], v[122:123], v[174:175], v[152:153] op_sel_hi:[1,0,1]
	v_pk_fma_f32 v[122:123], v[120:121], v[174:175], v[154:155] op_sel_hi:[1,0,1]
	v_cvt_pk_bf16_f32 v120, v124, v125
	v_lshl_add_u64 v[124:125], s[26:27], 0, v[232:233]
	v_cvt_pk_bf16_f32 v121, v126, v127
	v_lshl_add_u64 v[232:233], v[124:125], 0, v[220:221]
	v_lshlrev_b32_e32 v125, 16, v144
	v_and_b32_e32 v127, 0xffff0000, v144
	v_lshlrev_b32_e32 v144, 16, v145
	v_and_b32_e32 v145, 0xffff0000, v145
	v_cvt_pk_bf16_f32 v122, v122, v123
	v_cvt_pk_bf16_f32 v123, v152, v153
	v_lshlrev_b32_e32 v153, 16, v146
	v_and_b32_e32 v155, 0xffff0000, v146
	v_lshlrev_b32_e32 v165, 16, v147
	v_and_b32_e32 v181, 0xffff0000, v147
	v_sub_f32_e32 v145, v145, v204
	v_sub_f32_e32 v144, v144, v204
	v_sub_f32_e32 v147, v127, v204
	v_sub_f32_e32 v146, v125, v204
	v_pk_mul_f32 v[146:147], v[202:203], v[146:147] op_sel_hi:[0,1]
	v_pk_mul_f32 v[144:145], v[202:203], v[144:145] op_sel_hi:[0,1]
	v_pk_fma_f32 v[144:145], v[138:139], v[144:145], v[142:143]
	v_pk_fma_f32 v[146:147], v[136:137], v[146:147], v[140:141]
	v_pk_mul_f32 v[144:145], v[176:177], v[144:145] op_sel_hi:[0,1]
	v_pk_mul_f32 v[146:147], v[176:177], v[146:147] op_sel_hi:[0,1]
	v_pk_fma_f32 v[118:119], v[118:119], v[174:175], v[144:145] op_sel_hi:[1,0,1]
	v_pk_fma_f32 v[116:117], v[116:117], v[174:175], v[146:147] op_sel_hi:[1,0,1]
	v_sub_f32_e32 v145, v181, v204
	v_sub_f32_e32 v144, v165, v204
	v_sub_f32_e32 v147, v155, v204
	v_sub_f32_e32 v146, v153, v204
	v_pk_mul_f32 v[146:147], v[202:203], v[146:147] op_sel_hi:[0,1]
	v_pk_mul_f32 v[144:145], v[202:203], v[144:145] op_sel_hi:[0,1]
	v_pk_fma_f32 v[144:145], v[130:131], v[144:145], v[134:135]
	v_pk_fma_f32 v[146:147], v[128:129], v[146:147], v[132:133]
	v_pk_mul_f32 v[144:145], v[176:177], v[144:145] op_sel_hi:[0,1]
	v_pk_mul_f32 v[146:147], v[176:177], v[146:147] op_sel_hi:[0,1]
	v_pk_fma_f32 v[144:145], v[114:115], v[174:175], v[144:145] op_sel_hi:[1,0,1]
	v_pk_fma_f32 v[114:115], v[112:113], v[174:175], v[146:147] op_sel_hi:[1,0,1]
	v_cvt_pk_bf16_f32 v113, v118, v119
	v_lshlrev_b32_e32 v125, 16, v242
	v_and_b32_e32 v127, 0xffff0000, v242
	v_lshlrev_b32_e32 v118, 16, v243
	v_and_b32_e32 v119, 0xffff0000, v243
	v_cvt_pk_bf16_f32 v114, v114, v115
	v_cvt_pk_bf16_f32 v115, v144, v145
	v_sub_f32_e32 v119, v119, v200
	v_sub_f32_e32 v118, v118, v200
	v_sub_f32_e32 v145, v127, v200
	v_sub_f32_e32 v144, v125, v200
	v_pk_mul_f32 v[144:145], v[198:199], v[144:145] op_sel_hi:[0,1]
	v_pk_mul_f32 v[118:119], v[198:199], v[118:119] op_sel_hi:[0,1]
	v_pk_fma_f32 v[118:119], v[138:139], v[118:119], v[142:143]
	v_pk_fma_f32 v[144:145], v[136:137], v[144:145], v[140:141]
	v_lshlrev_b32_e32 v146, 16, v244
	v_and_b32_e32 v147, 0xffff0000, v244
	v_lshlrev_b32_e32 v153, 16, v245
	v_and_b32_e32 v155, 0xffff0000, v245
	v_pk_mul_f32 v[144:145], v[176:177], v[144:145] op_sel_hi:[0,1]
	v_pk_mul_f32 v[118:119], v[176:177], v[118:119] op_sel_hi:[0,1]
	v_pk_fma_f32 v[110:111], v[110:111], v[174:175], v[118:119] op_sel_hi:[1,0,1]
	v_pk_fma_f32 v[108:109], v[108:109], v[174:175], v[144:145] op_sel_hi:[1,0,1]
	v_sub_f32_e32 v119, v155, v200
	v_sub_f32_e32 v118, v153, v200
	v_sub_f32_e32 v145, v147, v200
	v_sub_f32_e32 v144, v146, v200
	v_pk_mul_f32 v[144:145], v[198:199], v[144:145] op_sel_hi:[0,1]
	v_pk_mul_f32 v[118:119], v[198:199], v[118:119] op_sel_hi:[0,1]
	v_pk_fma_f32 v[118:119], v[130:131], v[118:119], v[134:135]
	v_pk_fma_f32 v[144:145], v[128:129], v[144:145], v[132:133]
	v_pk_mul_f32 v[118:119], v[176:177], v[118:119] op_sel_hi:[0,1]
	v_pk_mul_f32 v[144:145], v[176:177], v[144:145] op_sel_hi:[0,1]
	v_pk_fma_f32 v[118:119], v[106:107], v[174:175], v[118:119] op_sel_hi:[1,0,1]
	v_pk_fma_f32 v[106:107], v[104:105], v[174:175], v[144:145] op_sel_hi:[1,0,1]
	v_cvt_pk_bf16_f32 v105, v110, v111
	v_lshlrev_b32_e32 v110, 16, v149
	v_cvt_pk_bf16_f32 v106, v106, v107
	v_cvt_pk_bf16_f32 v107, v118, v119
	v_lshlrev_b32_e32 v118, 16, v148
	v_and_b32_e32 v119, 0xffff0000, v148
	v_and_b32_e32 v111, 0xffff0000, v149
	v_sub_f32_e32 v111, v111, v196
	v_sub_f32_e32 v110, v110, v196
	v_sub_f32_e32 v119, v119, v196
	v_sub_f32_e32 v118, v118, v196
	v_pk_mul_f32 v[118:119], v[194:195], v[118:119] op_sel_hi:[0,1]
	v_pk_mul_f32 v[110:111], v[194:195], v[110:111] op_sel_hi:[0,1]
	v_pk_fma_f32 v[110:111], v[138:139], v[110:111], v[142:143]
	v_pk_fma_f32 v[118:119], v[136:137], v[118:119], v[140:141]
	v_lshlrev_b32_e32 v125, 16, v150
	v_and_b32_e32 v127, 0xffff0000, v150
	v_lshlrev_b32_e32 v144, 16, v151
	v_and_b32_e32 v145, 0xffff0000, v151
	v_pk_mul_f32 v[118:119], v[176:177], v[118:119] op_sel_hi:[0,1]
	v_pk_mul_f32 v[110:111], v[176:177], v[110:111] op_sel_hi:[0,1]
	v_pk_fma_f32 v[102:103], v[102:103], v[174:175], v[110:111] op_sel_hi:[1,0,1]
	v_pk_fma_f32 v[100:101], v[100:101], v[174:175], v[118:119] op_sel_hi:[1,0,1]
	v_sub_f32_e32 v111, v145, v196
	v_sub_f32_e32 v110, v144, v196
	v_sub_f32_e32 v119, v127, v196
	v_sub_f32_e32 v118, v125, v196
	v_pk_mul_f32 v[118:119], v[194:195], v[118:119] op_sel_hi:[0,1]
	v_pk_mul_f32 v[110:111], v[194:195], v[110:111] op_sel_hi:[0,1]
	v_pk_fma_f32 v[110:111], v[130:131], v[110:111], v[134:135]
	v_pk_fma_f32 v[118:119], v[128:129], v[118:119], v[132:133]
	v_pk_mul_f32 v[110:111], v[176:177], v[110:111] op_sel_hi:[0,1]
	v_pk_mul_f32 v[118:119], v[176:177], v[118:119] op_sel_hi:[0,1]
	v_cvt_pk_bf16_f32 v112, v116, v117
	v_lshl_add_u64 v[116:117], s[26:27], 0, v[236:237]
	v_cvt_pk_bf16_f32 v104, v108, v109
	v_lshl_add_u64 v[108:109], s[26:27], 0, v[240:241]
	v_pk_fma_f32 v[110:111], v[98:99], v[174:175], v[110:111] op_sel_hi:[1,0,1]
	v_pk_fma_f32 v[98:99], v[96:97], v[174:175], v[118:119] op_sel_hi:[1,0,1]
	v_cvt_pk_bf16_f32 v96, v100, v101
	v_lshl_add_u64 v[100:101], s[26:27], 0, v[238:239]
	v_lshl_add_u64 v[116:117], v[116:117], 0, v[220:221]
	v_lshl_add_u64 v[108:109], v[108:109], 0, v[220:221]
	v_lshl_add_u64 v[100:101], v[100:101], 0, v[220:221]
	global_store_dwordx4 v[232:233], v[120:123], off
	global_store_dwordx4 v[116:117], v[112:115], off
	global_store_dwordx4 v[108:109], v[104:107], off
	v_cvt_pk_bf16_f32 v97, v102, v103
	v_cvt_pk_bf16_f32 v98, v98, v99
	v_cvt_pk_bf16_f32 v99, v110, v111
	global_store_dwordx4 v[100:101], v[96:99], off
	v_lshlrev_b64 v[144:145], 11, v[222:223]
	v_lshl_add_u64 v[102:103], v[234:235], 0, v[144:145]
	global_load_dwordx4 v[236:239], v[102:103], off
	v_lshlrev_b64 v[146:147], 11, v[226:227]
	v_lshl_add_u64 v[110:111], v[234:235], 0, v[146:147]
	global_load_dwordx4 v[240:243], v[110:111], off
	v_lshlrev_b64 v[150:151], 11, v[210:211]
	v_lshl_add_u64 v[148:149], v[234:235], 0, v[150:151]
	global_load_dwordx4 v[244:247], v[148:149], off
	v_lshlrev_b64 v[210:211], 11, v[212:213]
	v_lshl_add_u64 v[118:119], v[234:235], 0, v[210:211]
	global_load_dwordx4 v[248:251], v[118:119], off
	v_and_b32_e32 v154, 0xffff0000, v120
	v_lshlrev_b32_e32 v152, 16, v121
	v_and_b32_e32 v126, 0xffff0000, v122
	v_lshlrev_b32_e32 v124, 16, v123
	s_waitcnt vmcnt(0)
; __device__ __forceinline__ unsigned cvt_pk_bf16(float lo, float hi) { unsigned r; asm("v_cvt_pk_bf16_f32 %0, %1, %2" : "=v"(r) : "v"(lo), "v"(hi)); return r; }
; __device__ __forceinline__ float bf_lo(unsigned w) { return __uint_as_float(w << 16); }
; __device__ __forceinline__ float bf_hi(unsigned w) { return __uint_as_float(w & 0xffff0000u); }
;     __device__ __forceinline__ void operator()(const f32x4 (&acc)[2][2][4][2], const Unit& u, int wr, int wc, int fr_in, int fq_in) const {
;     ...
;             for (int ai = 0; ai < 2; ++ai) {
;                 f32x4 pf[4][2]; u32x4 pb[4];
; #pragma unroll
;                 for (int m = 0; m < 4; ++m) { const size_t off = (size_t)(row0 + ai * HALF + m * 16) * 1024 + col0 + bj * HALF;
;                     if constexpr (BASE == 0) { pf[m][0] = *(const f32x4*)(basef + off); pf[m][1] = *(const f32x4*)(basef + off + 4); } else pb[m] = *(const u32x4*)(baseb + off); }
; #pragma unroll
;                 for (int m = 0; m < 4; ++m) { const size_t off = (size_t)(row0 + ai * HALF + m * 16) * 1024 + col0 + bj * HALF; f32x4 b[2];
;                     if constexpr (BASE == 0) { b[0] = pf[m][0]; b[1] = pf[m][1]; }
;                     else { const u32x4 pw = pb[m]; b[0] = (f32x4){bf_lo(pw.x), bf_hi(pw.x), bf_lo(pw.y), bf_hi(pw.y)}; b[1] = (f32x4){bf_lo(pw.z), bf_hi(pw.z), bf_lo(pw.w), bf_hi(pw.w)}; }
;                     f32x4 z[2];
; #pragma unroll
;                     for (int n = 0; n < 2; ++n) { if constexpr (BASE == 1) b[n] = (b[n] - rst.mu[ai][m]) * rst.rs[ai][m] * gv[n] + bv[n];
;                         z[n] = b[n] * al_ + acc[ai][bj][m][n] * s_; }
;                     u32x4 w; w.x = cvt_pk_bf16(z[0][0], z[0][1]); w.y = cvt_pk_bf16(z[0][2], z[0][3]); w.z = cvt_pk_bf16(z[1][0], z[1][1]); w.w = cvt_pk_bf16(z[1][2], z[1][3]);
;                     *(u32x4*)(zb + off) = w;
;                     const float r0 = bf_lo(w.x), r1 = bf_hi(w.x), r2 = bf_lo(w.y), r3 = bf_hi(w.y), r4 = bf_lo(w.z), r5 = bf_hi(w.z), r6 = bf_lo(w.w), r7 = bf_hi(w.w);
;                     s1[ai][m] += ((r0 + r1) + (r2 + r3)) + ((r4 + r5) + (r6 + r7)); s2[ai][m] += ((r0 * r0 + r1 * r1) + (r2 * r2 + r3 * r3)) + ((r4 * r4 + r5 * r5) + (r6 * r6 + r7 * r7)); }
	v_lshlrev_b32_e32 v125, 16, v236
	v_and_b32_e32 v127, 0xffff0000, v236
	v_lshlrev_b32_e32 v153, 16, v237
	v_and_b32_e32 v155, 0xffff0000, v237
	v_sub_f32_e32 v213, v155, v192
	v_sub_f32_e32 v212, v153, v192
	v_sub_f32_e32 v223, v127, v192
	v_sub_f32_e32 v222, v125, v192
	v_pk_mul_f32 v[222:223], v[190:191], v[222:223] op_sel_hi:[0,1]
	v_pk_mul_f32 v[212:213], v[190:191], v[212:213] op_sel_hi:[0,1]
	v_pk_fma_f32 v[212:213], v[138:139], v[212:213], v[142:143]
	v_pk_fma_f32 v[222:223], v[136:137], v[222:223], v[140:141]
	v_lshlrev_b32_e32 v165, 16, v238
	v_and_b32_e32 v181, 0xffff0000, v238
	v_lshlrev_b32_e32 v185, 16, v239
	v_and_b32_e32 v189, 0xffff0000, v239
	v_pk_mul_f32 v[222:223], v[176:177], v[222:223] op_sel_hi:[0,1]
	v_pk_mul_f32 v[212:213], v[176:177], v[212:213] op_sel_hi:[0,1]
	v_pk_fma_f32 v[94:95], v[94:95], v[174:175], v[212:213] op_sel_hi:[1,0,1]
	v_pk_fma_f32 v[92:93], v[92:93], v[174:175], v[222:223] op_sel_hi:[1,0,1]
	v_sub_f32_e32 v213, v189, v192
	v_sub_f32_e32 v212, v185, v192
	v_sub_f32_e32 v223, v181, v192
	v_sub_f32_e32 v222, v165, v192
	v_pk_mul_f32 v[222:223], v[190:191], v[222:223] op_sel_hi:[0,1]
	v_pk_mul_f32 v[212:213], v[190:191], v[212:213] op_sel_hi:[0,1]
	v_pk_fma_f32 v[212:213], v[130:131], v[212:213], v[134:135]
	v_pk_fma_f32 v[222:223], v[128:129], v[222:223], v[132:133]
	v_pk_mul_f32 v[212:213], v[176:177], v[212:213] op_sel_hi:[0,1]
	v_pk_mul_f32 v[222:223], v[176:177], v[222:223] op_sel_hi:[0,1]
	v_pk_fma_f32 v[212:213], v[90:91], v[174:175], v[212:213] op_sel_hi:[1,0,1]
	v_pk_fma_f32 v[90:91], v[88:89], v[174:175], v[222:223] op_sel_hi:[1,0,1]
	v_cvt_pk_bf16_f32 v88, v92, v93
	v_lshl_add_u64 v[92:93], s[26:27], 0, v[144:145]
	v_cvt_pk_bf16_f32 v89, v94, v95
	v_lshl_add_u64 v[144:145], v[92:93], 0, v[220:221]
	v_lshlrev_b32_e32 v94, 16, v240
	v_and_b32_e32 v95, 0xffff0000, v240
	v_lshlrev_b32_e32 v92, 16, v241
	v_and_b32_e32 v93, 0xffff0000, v241
	v_sub_f32_e32 v93, v93, v188
	v_sub_f32_e32 v92, v92, v188
	v_sub_f32_e32 v95, v95, v188
	v_sub_f32_e32 v94, v94, v188
	v_pk_mul_f32 v[94:95], v[186:187], v[94:95] op_sel_hi:[0,1]
	v_pk_mul_f32 v[92:93], v[186:187], v[92:93] op_sel_hi:[0,1]
	v_pk_fma_f32 v[92:93], v[138:139], v[92:93], v[142:143]
	v_pk_fma_f32 v[94:95], v[136:137], v[94:95], v[140:141]
	v_lshlrev_b32_e32 v125, 16, v242
	v_and_b32_e32 v127, 0xffff0000, v242
	v_lshlrev_b32_e32 v153, 16, v243
	v_and_b32_e32 v155, 0xffff0000, v243
	v_pk_mul_f32 v[94:95], v[176:177], v[94:95] op_sel_hi:[0,1]
	v_pk_mul_f32 v[92:93], v[176:177], v[92:93] op_sel_hi:[0,1]
	v_pk_fma_f32 v[86:87], v[86:87], v[174:175], v[92:93] op_sel_hi:[1,0,1]
	v_pk_fma_f32 v[84:85], v[84:85], v[174:175], v[94:95] op_sel_hi:[1,0,1]
	v_sub_f32_e32 v93, v155, v188
	v_sub_f32_e32 v92, v153, v188
	v_sub_f32_e32 v95, v127, v188
	v_sub_f32_e32 v94, v125, v188
	v_pk_mul_f32 v[94:95], v[186:187], v[94:95] op_sel_hi:[0,1]
	v_pk_mul_f32 v[92:93], v[186:187], v[92:93] op_sel_hi:[0,1]
	v_pk_fma_f32 v[92:93], v[130:131], v[92:93], v[134:135]
	v_pk_fma_f32 v[94:95], v[128:129], v[94:95], v[132:133]
	v_pk_mul_f32 v[92:93], v[176:177], v[92:93] op_sel_hi:[0,1]
	v_pk_mul_f32 v[94:95], v[176:177], v[94:95] op_sel_hi:[0,1]
	v_pk_fma_f32 v[92:93], v[82:83], v[174:175], v[92:93] op_sel_hi:[1,0,1]
	v_pk_fma_f32 v[82:83], v[80:81], v[174:175], v[94:95] op_sel_hi:[1,0,1]
	v_cvt_pk_bf16_f32 v80, v84, v85
	v_lshl_add_u64 v[84:85], s[26:27], 0, v[146:147]
	v_cvt_pk_bf16_f32 v81, v86, v87
	v_lshl_add_u64 v[146:147], v[84:85], 0, v[220:221]
	v_lshlrev_b32_e32 v86, 16, v244
	v_and_b32_e32 v87, 0xffff0000, v244
	v_lshlrev_b32_e32 v84, 16, v245
	v_and_b32_e32 v85, 0xffff0000, v245
	v_sub_f32_e32 v85, v85, v184
	v_sub_f32_e32 v84, v84, v184
	v_sub_f32_e32 v87, v87, v184
	v_sub_f32_e32 v86, v86, v184
	v_pk_mul_f32 v[86:87], v[182:183], v[86:87] op_sel_hi:[0,1]
	v_pk_mul_f32 v[84:85], v[182:183], v[84:85] op_sel_hi:[0,1]
	v_pk_fma_f32 v[84:85], v[138:139], v[84:85], v[142:143]
	v_pk_fma_f32 v[86:87], v[136:137], v[86:87], v[140:141]
	v_cvt_pk_bf16_f32 v82, v82, v83
	v_cvt_pk_bf16_f32 v83, v92, v93
	v_lshlrev_b32_e32 v92, 16, v246
	v_and_b32_e32 v93, 0xffff0000, v246
	v_lshlrev_b32_e32 v94, 16, v247
	v_and_b32_e32 v95, 0xffff0000, v247
	v_pk_mul_f32 v[86:87], v[176:177], v[86:87] op_sel_hi:[0,1]
	v_pk_mul_f32 v[84:85], v[176:177], v[84:85] op_sel_hi:[0,1]
	v_pk_fma_f32 v[78:79], v[78:79], v[174:175], v[84:85] op_sel_hi:[1,0,1]
	v_pk_fma_f32 v[76:77], v[76:77], v[174:175], v[86:87] op_sel_hi:[1,0,1]
	v_sub_f32_e32 v85, v95, v184
	v_sub_f32_e32 v84, v94, v184
	v_sub_f32_e32 v87, v93, v184
	v_sub_f32_e32 v86, v92, v184
	v_pk_mul_f32 v[86:87], v[182:183], v[86:87] op_sel_hi:[0,1]
	v_pk_mul_f32 v[84:85], v[182:183], v[84:85] op_sel_hi:[0,1]
	v_pk_fma_f32 v[84:85], v[130:131], v[84:85], v[134:135]
	v_pk_fma_f32 v[86:87], v[128:129], v[86:87], v[132:133]
	v_pk_mul_f32 v[84:85], v[176:177], v[84:85] op_sel_hi:[0,1]
	v_pk_mul_f32 v[86:87], v[176:177], v[86:87] op_sel_hi:[0,1]
	v_pk_fma_f32 v[84:85], v[74:75], v[174:175], v[84:85] op_sel_hi:[1,0,1]
	v_pk_fma_f32 v[74:75], v[72:73], v[174:175], v[86:87] op_sel_hi:[1,0,1]
	v_cvt_pk_bf16_f32 v72, v76, v77
	v_lshl_add_u64 v[76:77], s[26:27], 0, v[150:151]
	v_cvt_pk_bf16_f32 v73, v78, v79
	v_lshl_add_u64 v[150:151], v[76:77], 0, v[220:221]
	v_lshlrev_b32_e32 v78, 16, v248
	v_and_b32_e32 v79, 0xffff0000, v248
	v_lshlrev_b32_e32 v76, 16, v249
	v_and_b32_e32 v77, 0xffff0000, v249
	v_sub_f32_e32 v77, v77, v180
	v_sub_f32_e32 v76, v76, v180
	v_sub_f32_e32 v79, v79, v180
	v_sub_f32_e32 v78, v78, v180
	v_pk_mul_f32 v[78:79], v[178:179], v[78:79] op_sel_hi:[0,1]
	v_pk_mul_f32 v[76:77], v[178:179], v[76:77] op_sel_hi:[0,1]
; __device__ __forceinline__ unsigned cvt_pk_bf16(float lo, float hi) { unsigned r; asm("v_cvt_pk_bf16_f32 %0, %1, %2" : "=v"(r) : "v"(lo), "v"(hi)); return r; }
;     __device__ __forceinline__ void operator()(const f32x4 (&acc)[2][2][4][2], const Unit& u, int wr, int wc, int fr_in, int fq_in) const {
;     ...
;         for (int bj = 0; bj < 2; ++bj) { f32x4 gv[2], bv[2];
;             if constexpr (BASE == 1) {
; #pragma unroll
;                 for (int n = 0; n < 2; ++n) { gv[n] = *(const f32x4*)(lg + col0 + bj * HALF + 4 * n); bv[n] = *(const f32x4*)(lb + col0 + bj * HALF + 4 * n); } }
; #pragma unroll
;             for (int ai = 0; ai < 2; ++ai) {
;                 f32x4 pf[4][2]; u32x4 pb[4];
; #pragma unroll
;                 for (int m = 0; m < 4; ++m) { const size_t off = (size_t)(row0 + ai * HALF + m * 16) * 1024 + col0 + bj * HALF;
;                     if constexpr (BASE == 0) { pf[m][0] = *(const f32x4*)(basef + off); pf[m][1] = *(const f32x4*)(basef + off + 4); } else pb[m] = *(const u32x4*)(baseb + off); }
; #pragma unroll
;                 for (int m = 0; m < 4; ++m) { const size_t off = (size_t)(row0 + ai * HALF + m * 16) * 1024 + col0 + bj * HALF; f32x4 b[2];
;                     if constexpr (BASE == 0) { b[0] = pf[m][0]; b[1] = pf[m][1]; }
;                     else { const u32x4 pw = pb[m]; b[0] = (f32x4){bf_lo(pw.x), bf_hi(pw.x), bf_lo(pw.y), bf_hi(pw.y)}; b[1] = (f32x4){bf_lo(pw.z), bf_hi(pw.z), bf_lo(pw.w), bf_hi(pw.w)}; }
;                     f32x4 z[2];
; #pragma unroll
;                     for (int n = 0; n < 2; ++n) { if constexpr (BASE == 1) b[n] = (b[n] - rst.mu[ai][m]) * rst.rs[ai][m] * gv[n] + bv[n];
;                         z[n] = b[n] * al_ + acc[ai][bj][m][n] * s_; }
;                     u32x4 w; w.x = cvt_pk_bf16(z[0][0], z[0][1]); w.y = cvt_pk_bf16(z[0][2], z[0][3]); w.z = cvt_pk_bf16(z[1][0], z[1][1]); w.w = cvt_pk_bf16(z[1][2], z[1][3]);
;                     *(u32x4*)(zb + off) = w;
;                     const float r0 = bf_lo(w.x), r1 = bf_hi(w.x), r2 = bf_lo(w.y), r3 = bf_hi(w.y), r4 = bf_lo(w.z), r5 = bf_hi(w.z), r6 = bf_lo(w.w), r7 = bf_hi(w.w);
;                     s1[ai][m] += ((r0 + r1) + (r2 + r3)) + ((r4 + r5) + (r6 + r7)); s2[ai][m] += ((r0 * r0 + r1 * r1) + (r2 * r2 + r3 * r3)) + ((r4 * r4 + r5 * r5) + (r6 * r6 + r7 * r7)); }
	v_pk_fma_f32 v[76:77], v[138:139], v[76:77], v[142:143]
	v_pk_fma_f32 v[78:79], v[136:137], v[78:79], v[140:141]
	v_cvt_pk_bf16_f32 v74, v74, v75
	v_cvt_pk_bf16_f32 v75, v84, v85
	v_lshlrev_b32_e32 v84, 16, v250
	v_and_b32_e32 v85, 0xffff0000, v250
	v_lshlrev_b32_e32 v86, 16, v251
	v_and_b32_e32 v87, 0xffff0000, v251
	v_pk_mul_f32 v[78:79], v[176:177], v[78:79] op_sel_hi:[0,1]
	v_pk_mul_f32 v[76:77], v[176:177], v[76:77] op_sel_hi:[0,1]
	v_pk_fma_f32 v[70:71], v[70:71], v[174:175], v[76:77] op_sel_hi:[1,0,1]
	v_pk_fma_f32 v[68:69], v[68:69], v[174:175], v[78:79] op_sel_hi:[1,0,1]
	v_sub_f32_e32 v77, v87, v180
	v_sub_f32_e32 v76, v86, v180
	v_sub_f32_e32 v79, v85, v180
	v_sub_f32_e32 v78, v84, v180
	v_pk_mul_f32 v[78:79], v[178:179], v[78:79] op_sel_hi:[0,1]
	v_pk_mul_f32 v[76:77], v[178:179], v[76:77] op_sel_hi:[0,1]
	v_pk_fma_f32 v[76:77], v[130:131], v[76:77], v[134:135]
	v_pk_fma_f32 v[78:79], v[128:129], v[78:79], v[132:133]
	v_pk_mul_f32 v[76:77], v[176:177], v[76:77] op_sel_hi:[0,1]
	v_pk_mul_f32 v[78:79], v[176:177], v[78:79] op_sel_hi:[0,1]
	v_pk_fma_f32 v[76:77], v[66:67], v[174:175], v[76:77] op_sel_hi:[1,0,1]
	v_pk_fma_f32 v[66:67], v[64:65], v[174:175], v[78:79] op_sel_hi:[1,0,1]
	v_cvt_pk_bf16_f32 v64, v68, v69
	v_lshl_add_u64 v[68:69], s[26:27], 0, v[210:211]
	v_lshl_add_u64 v[128:129], v[68:69], 0, v[220:221]
	v_cvt_pk_bf16_f32 v90, v90, v91
	v_cvt_pk_bf16_f32 v91, v212, v213
	global_store_dwordx4 v[144:145], v[88:91], off
	global_store_dwordx4 v[146:147], v[80:83], off
	global_store_dwordx4 v[150:151], v[72:75], off
	v_cvt_pk_bf16_f32 v65, v70, v71
	v_cvt_pk_bf16_f32 v66, v66, v67
	v_cvt_pk_bf16_f32 v67, v76, v77
	global_store_dwordx4 v[128:129], v[64:67], off
	global_load_dwordx4 v[68:71], v[216:217], off offset:528
	global_load_dwordx4 v[84:87], v[216:217], off offset:512
	global_load_dwordx4 v[76:79], v[214:215], off offset:528
	global_load_dwordx4 v[92:95], v[214:215], off offset:512
	global_load_dwordx4 v[130:133], v[218:219], off offset:256
	global_load_dwordx4 v[134:137], v[224:225], off offset:256
	global_load_dwordx4 v[138:141], v[228:229], off offset:256
	global_load_dwordx4 v[210:213], v[230:231], off offset:256
	s_waitcnt vmcnt(0)
	v_lshlrev_b32_e32 v125, 16, v130
	v_and_b32_e32 v127, 0xffff0000, v130
	v_lshlrev_b32_e32 v130, 16, v131
	v_and_b32_e32 v131, 0xffff0000, v131
	v_lshlrev_b32_e32 v142, 16, v132
	v_and_b32_e32 v143, 0xffff0000, v132
	v_lshlrev_b32_e32 v153, 16, v133
	v_and_b32_e32 v155, 0xffff0000, v133
	v_sub_f32_e32 v131, v131, v208
	v_sub_f32_e32 v130, v130, v208
	v_sub_f32_e32 v133, v127, v208
	v_sub_f32_e32 v132, v125, v208
	v_pk_mul_f32 v[132:133], v[206:207], v[132:133] op_sel_hi:[0,1]
	v_pk_mul_f32 v[130:131], v[206:207], v[130:131] op_sel_hi:[0,1]
	v_pk_fma_f32 v[130:131], v[86:87], v[130:131], v[94:95]
	v_pk_fma_f32 v[132:133], v[84:85], v[132:133], v[92:93]
	v_pk_mul_f32 v[130:131], v[176:177], v[130:131] op_sel_hi:[0,1]
	v_pk_mul_f32 v[132:133], v[176:177], v[132:133] op_sel_hi:[0,1]
	v_pk_fma_f32 v[62:63], v[62:63], v[174:175], v[130:131] op_sel_hi:[1,0,1]
	v_pk_fma_f32 v[60:61], v[60:61], v[174:175], v[132:133] op_sel_hi:[1,0,1]
	v_sub_f32_e32 v131, v155, v208
	v_sub_f32_e32 v130, v153, v208
	v_sub_f32_e32 v133, v143, v208
	v_sub_f32_e32 v132, v142, v208
	v_pk_mul_f32 v[132:133], v[206:207], v[132:133] op_sel_hi:[0,1]
	v_pk_mul_f32 v[130:131], v[206:207], v[130:131] op_sel_hi:[0,1]
	v_pk_fma_f32 v[130:131], v[70:71], v[130:131], v[78:79]
	v_pk_fma_f32 v[132:133], v[68:69], v[132:133], v[76:77]
	v_pk_mul_f32 v[130:131], v[176:177], v[130:131] op_sel_hi:[0,1]
	v_pk_mul_f32 v[132:133], v[176:177], v[132:133] op_sel_hi:[0,1]
	v_pk_fma_f32 v[130:131], v[58:59], v[174:175], v[130:131] op_sel_hi:[1,0,1]
	v_pk_fma_f32 v[58:59], v[56:57], v[174:175], v[132:133] op_sel_hi:[1,0,1]
	v_cvt_pk_bf16_f32 v57, v62, v63
	v_cvt_pk_bf16_f32 v56, v60, v61
	v_and_b32_e32 v125, 0xffff0000, v134
	v_cvt_pk_bf16_f32 v58, v58, v59
	v_cvt_pk_bf16_f32 v59, v130, v131
	global_store_dwordx4 v[232:233], v[56:59], off offset:256
	v_and_b32_e32 v63, 0xffff0000, v59
	v_and_b32_e32 v62, 0xffff0000, v58
	v_lshlrev_b32_e32 v61, 16, v59
	v_lshlrev_b32_e32 v60, 16, v58
	v_pk_mul_f32 v[58:59], v[62:63], v[62:63]
	v_lshlrev_b32_e32 v127, 16, v135
	v_pk_fma_f32 v[58:59], v[60:61], v[60:61], v[58:59]
	v_and_b32_e32 v130, 0xffff0000, v135
	v_pk_add_f32 v[58:59], v[58:59], v[58:59] op_sel_hi:[0,1]
	v_lshlrev_b32_e32 v58, 16, v134
	v_sub_f32_e32 v131, v130, v204
	v_sub_f32_e32 v130, v127, v204
	v_sub_f32_e32 v133, v125, v204
	v_sub_f32_e32 v132, v58, v204
	v_pk_mul_f32 v[132:133], v[202:203], v[132:133] op_sel_hi:[0,1]
	v_pk_mul_f32 v[130:131], v[202:203], v[130:131] op_sel_hi:[0,1]
	v_pk_fma_f32 v[130:131], v[86:87], v[130:131], v[94:95]
	v_pk_fma_f32 v[132:133], v[84:85], v[132:133], v[92:93]
	v_lshlrev_b32_e32 v134, 16, v136
	v_and_b32_e32 v135, 0xffff0000, v136
	v_lshlrev_b32_e32 v136, 16, v137
	v_and_b32_e32 v137, 0xffff0000, v137
	v_pk_mul_f32 v[132:133], v[176:177], v[132:133] op_sel_hi:[0,1]
	v_pk_mul_f32 v[130:131], v[176:177], v[130:131] op_sel_hi:[0,1]
	v_pk_fma_f32 v[54:55], v[54:55], v[174:175], v[130:131] op_sel_hi:[1,0,1]
	v_pk_fma_f32 v[52:53], v[52:53], v[174:175], v[132:133] op_sel_hi:[1,0,1]
	v_sub_f32_e32 v131, v137, v204
	v_sub_f32_e32 v130, v136, v204
	v_sub_f32_e32 v133, v135, v204
	v_sub_f32_e32 v132, v134, v204
	v_pk_mul_f32 v[132:133], v[202:203], v[132:133] op_sel_hi:[0,1]
	v_pk_mul_f32 v[130:131], v[202:203], v[130:131] op_sel_hi:[0,1]
	v_pk_fma_f32 v[130:131], v[70:71], v[130:131], v[78:79]
	v_pk_fma_f32 v[132:133], v[68:69], v[132:133], v[76:77]
	v_pk_mul_f32 v[130:131], v[176:177], v[130:131] op_sel_hi:[0,1]
; __device__ __forceinline__ unsigned cvt_pk_bf16(float lo, float hi) { unsigned r; asm("v_cvt_pk_bf16_f32 %0, %1, %2" : "=v"(r) : "v"(lo), "v"(hi)); return r; }
; __device__ __forceinline__ float bf_lo(unsigned w) { return __uint_as_float(w << 16); }
; __device__ __forceinline__ float bf_hi(unsigned w) { return __uint_as_float(w & 0xffff0000u); }
;     __device__ __forceinline__ void operator()(const f32x4 (&acc)[2][2][4][2], const Unit& u, int wr, int wc, int fr_in, int fq_in) const {
;     ...
;             for (int ai = 0; ai < 2; ++ai) {
;                 f32x4 pf[4][2]; u32x4 pb[4];
; #pragma unroll
;                 for (int m = 0; m < 4; ++m) { const size_t off = (size_t)(row0 + ai * HALF + m * 16) * 1024 + col0 + bj * HALF;
;                     if constexpr (BASE == 0) { pf[m][0] = *(const f32x4*)(basef + off); pf[m][1] = *(const f32x4*)(basef + off + 4); } else pb[m] = *(const u32x4*)(baseb + off); }
; #pragma unroll
;                 for (int m = 0; m < 4; ++m) { const size_t off = (size_t)(row0 + ai * HALF + m * 16) * 1024 + col0 + bj * HALF; f32x4 b[2];
;                     if constexpr (BASE == 0) { b[0] = pf[m][0]; b[1] = pf[m][1]; }
;                     else { const u32x4 pw = pb[m]; b[0] = (f32x4){bf_lo(pw.x), bf_hi(pw.x), bf_lo(pw.y), bf_hi(pw.y)}; b[1] = (f32x4){bf_lo(pw.z), bf_hi(pw.z), bf_lo(pw.w), bf_hi(pw.w)}; }
;                     f32x4 z[2];
; #pragma unroll
;                     for (int n = 0; n < 2; ++n) { if constexpr (BASE == 1) b[n] = (b[n] - rst.mu[ai][m]) * rst.rs[ai][m] * gv[n] + bv[n];
;                         z[n] = b[n] * al_ + acc[ai][bj][m][n] * s_; }
;                     u32x4 w; w.x = cvt_pk_bf16(z[0][0], z[0][1]); w.y = cvt_pk_bf16(z[0][2], z[0][3]); w.z = cvt_pk_bf16(z[1][0], z[1][1]); w.w = cvt_pk_bf16(z[1][2], z[1][3]);
;                     *(u32x4*)(zb + off) = w;
;                     const float r0 = bf_lo(w.x), r1 = bf_hi(w.x), r2 = bf_lo(w.y), r3 = bf_hi(w.y), r4 = bf_lo(w.z), r5 = bf_hi(w.z), r6 = bf_lo(w.w), r7 = bf_hi(w.w);
;                     s1[ai][m] += ((r0 + r1) + (r2 + r3)) + ((r4 + r5) + (r6 + r7)); s2[ai][m] += ((r0 * r0 + r1 * r1) + (r2 * r2 + r3 * r3)) + ((r4 * r4 + r5 * r5) + (r6 * r6 + r7 * r7)); }
	v_pk_mul_f32 v[132:133], v[176:177], v[132:133] op_sel_hi:[0,1]
	v_pk_fma_f32 v[130:131], v[50:51], v[174:175], v[130:131] op_sel_hi:[1,0,1]
	v_pk_fma_f32 v[50:51], v[48:49], v[174:175], v[132:133] op_sel_hi:[1,0,1]
	v_cvt_pk_bf16_f32 v48, v52, v53
	v_cvt_pk_bf16_f32 v49, v54, v55
	v_lshlrev_b32_e32 v54, 16, v138
	v_and_b32_e32 v55, 0xffff0000, v138
	v_lshlrev_b32_e32 v52, 16, v139
	v_and_b32_e32 v53, 0xffff0000, v139
	v_sub_f32_e32 v53, v53, v200
	v_sub_f32_e32 v52, v52, v200
	v_sub_f32_e32 v55, v55, v200
	v_sub_f32_e32 v54, v54, v200
	v_pk_mul_f32 v[54:55], v[198:199], v[54:55] op_sel_hi:[0,1]
	v_pk_mul_f32 v[52:53], v[198:199], v[52:53] op_sel_hi:[0,1]
	v_pk_fma_f32 v[52:53], v[86:87], v[52:53], v[94:95]
	v_pk_fma_f32 v[54:55], v[84:85], v[54:55], v[92:93]
	v_cvt_pk_bf16_f32 v50, v50, v51
	v_cvt_pk_bf16_f32 v51, v130, v131
	global_store_dwordx4 v[116:117], v[48:51], off offset:256
	v_lshlrev_b32_e32 v58, 16, v140
	v_and_b32_e32 v116, 0xffff0000, v140
	v_lshlrev_b32_e32 v117, 16, v141
	v_and_b32_e32 v125, 0xffff0000, v141
	v_pk_mul_f32 v[54:55], v[176:177], v[54:55] op_sel_hi:[0,1]
	v_pk_mul_f32 v[52:53], v[176:177], v[52:53] op_sel_hi:[0,1]
	v_pk_fma_f32 v[46:47], v[46:47], v[174:175], v[52:53] op_sel_hi:[1,0,1]
	v_pk_fma_f32 v[44:45], v[44:45], v[174:175], v[54:55] op_sel_hi:[1,0,1]
	v_sub_f32_e32 v53, v125, v200
	v_sub_f32_e32 v52, v117, v200
	v_sub_f32_e32 v55, v116, v200
	v_sub_f32_e32 v54, v58, v200
	v_pk_mul_f32 v[54:55], v[198:199], v[54:55] op_sel_hi:[0,1]
	v_pk_mul_f32 v[52:53], v[198:199], v[52:53] op_sel_hi:[0,1]
	v_pk_fma_f32 v[52:53], v[70:71], v[52:53], v[78:79]
	v_pk_fma_f32 v[54:55], v[68:69], v[54:55], v[76:77]
	v_pk_mul_f32 v[52:53], v[176:177], v[52:53] op_sel_hi:[0,1]
	v_pk_mul_f32 v[54:55], v[176:177], v[54:55] op_sel_hi:[0,1]
	v_pk_fma_f32 v[52:53], v[42:43], v[174:175], v[52:53] op_sel_hi:[1,0,1]
	v_pk_fma_f32 v[42:43], v[40:41], v[174:175], v[54:55] op_sel_hi:[1,0,1]
	v_cvt_pk_bf16_f32 v40, v44, v45
	v_cvt_pk_bf16_f32 v41, v46, v47
	v_lshlrev_b32_e32 v46, 16, v210
	v_and_b32_e32 v47, 0xffff0000, v210
	v_lshlrev_b32_e32 v44, 16, v211
	v_and_b32_e32 v45, 0xffff0000, v211
	v_sub_f32_e32 v45, v45, v196
	v_sub_f32_e32 v44, v44, v196
	v_sub_f32_e32 v47, v47, v196
	v_sub_f32_e32 v46, v46, v196
	v_pk_mul_f32 v[46:47], v[194:195], v[46:47] op_sel_hi:[0,1]
	v_pk_mul_f32 v[44:45], v[194:195], v[44:45] op_sel_hi:[0,1]
	v_pk_fma_f32 v[44:45], v[86:87], v[44:45], v[94:95]
	v_pk_fma_f32 v[46:47], v[84:85], v[46:47], v[92:93]
	v_cvt_pk_bf16_f32 v42, v42, v43
	v_cvt_pk_bf16_f32 v43, v52, v53
	v_lshlrev_b32_e32 v52, 16, v212
	v_and_b32_e32 v53, 0xffff0000, v212
	v_lshlrev_b32_e32 v54, 16, v213
	v_and_b32_e32 v55, 0xffff0000, v213
	v_pk_mul_f32 v[46:47], v[176:177], v[46:47] op_sel_hi:[0,1]
	v_pk_mul_f32 v[44:45], v[176:177], v[44:45] op_sel_hi:[0,1]
	v_pk_fma_f32 v[38:39], v[38:39], v[174:175], v[44:45] op_sel_hi:[1,0,1]
	v_pk_fma_f32 v[36:37], v[36:37], v[174:175], v[46:47] op_sel_hi:[1,0,1]
	v_sub_f32_e32 v45, v55, v196
	v_sub_f32_e32 v44, v54, v196
	v_sub_f32_e32 v47, v53, v196
	v_sub_f32_e32 v46, v52, v196
	v_pk_mul_f32 v[46:47], v[194:195], v[46:47] op_sel_hi:[0,1]
	v_pk_mul_f32 v[44:45], v[194:195], v[44:45] op_sel_hi:[0,1]
	v_pk_fma_f32 v[44:45], v[70:71], v[44:45], v[78:79]
	v_pk_fma_f32 v[46:47], v[68:69], v[46:47], v[76:77]
	v_pk_mul_f32 v[44:45], v[176:177], v[44:45] op_sel_hi:[0,1]
	v_pk_mul_f32 v[46:47], v[176:177], v[46:47] op_sel_hi:[0,1]
	v_pk_fma_f32 v[44:45], v[34:35], v[174:175], v[44:45] op_sel_hi:[1,0,1]
	v_pk_fma_f32 v[34:35], v[32:33], v[174:175], v[46:47] op_sel_hi:[1,0,1]
	global_store_dwordx4 v[108:109], v[40:43], off offset:256
	v_cvt_pk_bf16_f32 v32, v36, v37
	v_cvt_pk_bf16_f32 v33, v38, v39
	v_cvt_pk_bf16_f32 v34, v34, v35
	v_cvt_pk_bf16_f32 v35, v44, v45
	global_store_dwordx4 v[100:101], v[32:35], off offset:256
	global_load_dwordx4 v[36:39], v[102:103], off offset:256
	global_load_dwordx4 v[44:47], v[110:111], off offset:256
	global_load_dwordx4 v[52:55], v[148:149], off offset:256
	s_nop 0
	global_load_dwordx4 v[100:103], v[118:119], off offset:256
	v_mov_b32_e32 v165, v59
	s_waitcnt vmcnt(0)
	v_lshlrev_b32_e32 v58, 16, v36
	v_and_b32_e32 v108, 0xffff0000, v36
	v_lshlrev_b32_e32 v36, 16, v37
	v_and_b32_e32 v37, 0xffff0000, v37
	v_lshlrev_b32_e32 v109, 16, v38
	v_and_b32_e32 v110, 0xffff0000, v38
	v_lshlrev_b32_e32 v111, 16, v39
	v_and_b32_e32 v116, 0xffff0000, v39
	v_sub_f32_e32 v37, v37, v192
	v_sub_f32_e32 v36, v36, v192
	v_sub_f32_e32 v39, v108, v192
	v_sub_f32_e32 v38, v58, v192
	v_pk_mul_f32 v[38:39], v[190:191], v[38:39] op_sel_hi:[0,1]
	v_pk_mul_f32 v[36:37], v[190:191], v[36:37] op_sel_hi:[0,1]
	v_pk_fma_f32 v[36:37], v[86:87], v[36:37], v[94:95]
	v_pk_fma_f32 v[38:39], v[84:85], v[38:39], v[92:93]
	v_pk_mul_f32 v[36:37], v[176:177], v[36:37] op_sel_hi:[0,1]
	v_pk_mul_f32 v[38:39], v[176:177], v[38:39] op_sel_hi:[0,1]
	v_pk_fma_f32 v[30:31], v[30:31], v[174:175], v[36:37] op_sel_hi:[1,0,1]
	v_pk_fma_f32 v[28:29], v[28:29], v[174:175], v[38:39] op_sel_hi:[1,0,1]
	v_sub_f32_e32 v37, v116, v192
	v_sub_f32_e32 v36, v111, v192
	v_sub_f32_e32 v39, v110, v192
	v_sub_f32_e32 v38, v109, v192
	v_pk_mul_f32 v[38:39], v[190:191], v[38:39] op_sel_hi:[0,1]
	v_pk_mul_f32 v[36:37], v[190:191], v[36:37] op_sel_hi:[0,1]
	v_pk_fma_f32 v[36:37], v[70:71], v[36:37], v[78:79]
	v_pk_fma_f32 v[38:39], v[68:69], v[38:39], v[76:77]
	v_pk_mul_f32 v[36:37], v[176:177], v[36:37] op_sel_hi:[0,1]
	v_pk_mul_f32 v[38:39], v[176:177], v[38:39] op_sel_hi:[0,1]
	v_pk_fma_f32 v[36:37], v[26:27], v[174:175], v[36:37] op_sel_hi:[1,0,1]
	v_pk_fma_f32 v[26:27], v[24:25], v[174:175], v[38:39] op_sel_hi:[1,0,1]
; __device__ __forceinline__ unsigned cvt_pk_bf16(float lo, float hi) { unsigned r; asm("v_cvt_pk_bf16_f32 %0, %1, %2" : "=v"(r) : "v"(lo), "v"(hi)); return r; }
; __device__ __forceinline__ float bf_lo(unsigned w) { return __uint_as_float(w << 16); }
; __device__ __forceinline__ float bf_hi(unsigned w) { return __uint_as_float(w & 0xffff0000u); }
;     __device__ __forceinline__ void operator()(const f32x4 (&acc)[2][2][4][2], const Unit& u, int wr, int wc, int fr_in, int fq_in) const {
;     ...
;             for (int ai = 0; ai < 2; ++ai) {
;                 f32x4 pf[4][2]; u32x4 pb[4];
; #pragma unroll
;                 for (int m = 0; m < 4; ++m) { const size_t off = (size_t)(row0 + ai * HALF + m * 16) * 1024 + col0 + bj * HALF;
;                     if constexpr (BASE == 0) { pf[m][0] = *(const f32x4*)(basef + off); pf[m][1] = *(const f32x4*)(basef + off + 4); } else pb[m] = *(const u32x4*)(baseb + off); }
; #pragma unroll
;                 for (int m = 0; m < 4; ++m) { const size_t off = (size_t)(row0 + ai * HALF + m * 16) * 1024 + col0 + bj * HALF; f32x4 b[2];
;                     if constexpr (BASE == 0) { b[0] = pf[m][0]; b[1] = pf[m][1]; }
;                     else { const u32x4 pw = pb[m]; b[0] = (f32x4){bf_lo(pw.x), bf_hi(pw.x), bf_lo(pw.y), bf_hi(pw.y)}; b[1] = (f32x4){bf_lo(pw.z), bf_hi(pw.z), bf_lo(pw.w), bf_hi(pw.w)}; }
;                     f32x4 z[2];
; #pragma unroll
;                     for (int n = 0; n < 2; ++n) { if constexpr (BASE == 1) b[n] = (b[n] - rst.mu[ai][m]) * rst.rs[ai][m] * gv[n] + bv[n];
;                         z[n] = b[n] * al_ + acc[ai][bj][m][n] * s_; }
;                     u32x4 w; w.x = cvt_pk_bf16(z[0][0], z[0][1]); w.y = cvt_pk_bf16(z[0][2], z[0][3]); w.z = cvt_pk_bf16(z[1][0], z[1][1]); w.w = cvt_pk_bf16(z[1][2], z[1][3]);
;                     *(u32x4*)(zb + off) = w;
;                     const float r0 = bf_lo(w.x), r1 = bf_hi(w.x), r2 = bf_lo(w.y), r3 = bf_hi(w.y), r4 = bf_lo(w.z), r5 = bf_hi(w.z), r6 = bf_lo(w.w), r7 = bf_hi(w.w);
;                     s1[ai][m] += ((r0 + r1) + (r2 + r3)) + ((r4 + r5) + (r6 + r7)); s2[ai][m] += ((r0 * r0 + r1 * r1) + (r2 * r2 + r3 * r3)) + ((r4 * r4 + r5 * r5) + (r6 * r6 + r7 * r7)); }
	v_cvt_pk_bf16_f32 v24, v28, v29
	v_cvt_pk_bf16_f32 v25, v30, v31
	v_lshlrev_b32_e32 v30, 16, v44
	v_and_b32_e32 v31, 0xffff0000, v44
	v_lshlrev_b32_e32 v28, 16, v45
	v_and_b32_e32 v29, 0xffff0000, v45
	v_sub_f32_e32 v29, v29, v188
	v_sub_f32_e32 v28, v28, v188
	v_sub_f32_e32 v31, v31, v188
	v_sub_f32_e32 v30, v30, v188
	v_pk_mul_f32 v[30:31], v[186:187], v[30:31] op_sel_hi:[0,1]
	v_pk_mul_f32 v[28:29], v[186:187], v[28:29] op_sel_hi:[0,1]
	v_pk_fma_f32 v[28:29], v[86:87], v[28:29], v[94:95]
	v_pk_fma_f32 v[30:31], v[84:85], v[30:31], v[92:93]
	v_cvt_pk_bf16_f32 v26, v26, v27
	v_cvt_pk_bf16_f32 v27, v36, v37
	v_lshlrev_b32_e32 v36, 16, v46
	v_and_b32_e32 v37, 0xffff0000, v46
	v_lshlrev_b32_e32 v38, 16, v47
	v_and_b32_e32 v39, 0xffff0000, v47
	v_pk_mul_f32 v[30:31], v[176:177], v[30:31] op_sel_hi:[0,1]
	v_pk_mul_f32 v[28:29], v[176:177], v[28:29] op_sel_hi:[0,1]
	v_pk_fma_f32 v[22:23], v[22:23], v[174:175], v[28:29] op_sel_hi:[1,0,1]
	v_pk_fma_f32 v[20:21], v[20:21], v[174:175], v[30:31] op_sel_hi:[1,0,1]
	v_sub_f32_e32 v29, v39, v188
	v_sub_f32_e32 v28, v38, v188
	v_sub_f32_e32 v31, v37, v188
	v_sub_f32_e32 v30, v36, v188
	v_pk_mul_f32 v[30:31], v[186:187], v[30:31] op_sel_hi:[0,1]
	v_pk_mul_f32 v[28:29], v[186:187], v[28:29] op_sel_hi:[0,1]
	v_pk_fma_f32 v[28:29], v[70:71], v[28:29], v[78:79]
	v_pk_fma_f32 v[30:31], v[68:69], v[30:31], v[76:77]
	v_pk_mul_f32 v[28:29], v[176:177], v[28:29] op_sel_hi:[0,1]
	v_pk_mul_f32 v[30:31], v[176:177], v[30:31] op_sel_hi:[0,1]
	v_pk_fma_f32 v[28:29], v[18:19], v[174:175], v[28:29] op_sel_hi:[1,0,1]
	v_pk_fma_f32 v[18:19], v[16:17], v[174:175], v[30:31] op_sel_hi:[1,0,1]
	v_cvt_pk_bf16_f32 v16, v20, v21
	v_cvt_pk_bf16_f32 v17, v22, v23
	v_lshlrev_b32_e32 v22, 16, v52
	v_and_b32_e32 v23, 0xffff0000, v52
	v_lshlrev_b32_e32 v20, 16, v53
	v_and_b32_e32 v21, 0xffff0000, v53
	v_sub_f32_e32 v21, v21, v184
	v_sub_f32_e32 v20, v20, v184
	v_sub_f32_e32 v23, v23, v184
	v_sub_f32_e32 v22, v22, v184
	v_pk_mul_f32 v[22:23], v[182:183], v[22:23] op_sel_hi:[0,1]
	v_pk_mul_f32 v[20:21], v[182:183], v[20:21] op_sel_hi:[0,1]
	v_pk_fma_f32 v[20:21], v[86:87], v[20:21], v[94:95]
	v_pk_fma_f32 v[22:23], v[84:85], v[22:23], v[92:93]
	v_cvt_pk_bf16_f32 v18, v18, v19
	v_cvt_pk_bf16_f32 v19, v28, v29
	v_lshlrev_b32_e32 v28, 16, v54
	v_and_b32_e32 v29, 0xffff0000, v54
	v_lshlrev_b32_e32 v30, 16, v55
	v_and_b32_e32 v31, 0xffff0000, v55
	v_pk_mul_f32 v[22:23], v[176:177], v[22:23] op_sel_hi:[0,1]
	v_pk_mul_f32 v[20:21], v[176:177], v[20:21] op_sel_hi:[0,1]
	v_pk_fma_f32 v[14:15], v[14:15], v[174:175], v[20:21] op_sel_hi:[1,0,1]
	v_pk_fma_f32 v[12:13], v[12:13], v[174:175], v[22:23] op_sel_hi:[1,0,1]
	v_sub_f32_e32 v21, v31, v184
	v_sub_f32_e32 v20, v30, v184
	v_sub_f32_e32 v23, v29, v184
	v_sub_f32_e32 v22, v28, v184
	v_pk_mul_f32 v[22:23], v[182:183], v[22:23] op_sel_hi:[0,1]
	v_pk_mul_f32 v[20:21], v[182:183], v[20:21] op_sel_hi:[0,1]
	v_pk_fma_f32 v[20:21], v[70:71], v[20:21], v[78:79]
	v_pk_fma_f32 v[22:23], v[68:69], v[22:23], v[76:77]
	v_pk_mul_f32 v[20:21], v[176:177], v[20:21] op_sel_hi:[0,1]
	v_pk_mul_f32 v[22:23], v[176:177], v[22:23] op_sel_hi:[0,1]
	v_pk_fma_f32 v[20:21], v[10:11], v[174:175], v[20:21] op_sel_hi:[1,0,1]
	v_pk_fma_f32 v[10:11], v[8:9], v[174:175], v[22:23] op_sel_hi:[1,0,1]
	v_cvt_pk_bf16_f32 v8, v12, v13
	v_cvt_pk_bf16_f32 v9, v14, v15
	v_lshlrev_b32_e32 v14, 16, v100
	v_and_b32_e32 v15, 0xffff0000, v100
	v_lshlrev_b32_e32 v12, 16, v101
	v_and_b32_e32 v13, 0xffff0000, v101
	v_sub_f32_e32 v13, v13, v180
	v_sub_f32_e32 v12, v12, v180
	v_sub_f32_e32 v15, v15, v180
	v_sub_f32_e32 v14, v14, v180
	v_pk_mul_f32 v[14:15], v[178:179], v[14:15] op_sel_hi:[0,1]
	v_pk_mul_f32 v[12:13], v[178:179], v[12:13] op_sel_hi:[0,1]
	v_pk_fma_f32 v[12:13], v[86:87], v[12:13], v[94:95]
	v_pk_fma_f32 v[14:15], v[84:85], v[14:15], v[92:93]
	v_cvt_pk_bf16_f32 v10, v10, v11
	v_cvt_pk_bf16_f32 v11, v20, v21
	v_lshlrev_b32_e32 v20, 16, v102
; __device__ __forceinline__ unsigned cvt_pk_bf16(float lo, float hi) { unsigned r; asm("v_cvt_pk_bf16_f32 %0, %1, %2" : "=v"(r) : "v"(lo), "v"(hi)); return r; }
; __device__ __forceinline__ float bf_lo(unsigned w) { return __uint_as_float(w << 16); }
; __device__ __forceinline__ float bf_hi(unsigned w) { return __uint_as_float(w & 0xffff0000u); }
; __device__ __forceinline__ void emit_row_stats(float (&s1)[2][4], float (&s2)[2][4], float* sp_new, const Unit& u, int wr, int wc, int fr, int fq, PG8_LAS unsigned char* xl) {
;     ...
;         for (int m = 0; m < 4; ++m) { float a = s1[ai][m], b = s2[ai][m]; a += __shfl_xor(a, 16); b += __shfl_xor(b, 16); a += __shfl_xor(a, 32); b += __shfl_xor(b, 32);
;             if (fq == 0) P[(ai * HALF + wr * 64 + m * 16 + fr) * 4 + wc] = (f32x2v){a, b}; }
;     __device__ __forceinline__ void operator()(const f32x4 (&acc)[2][2][4][2], const Unit& u, int wr, int wc, int fr_in, int fq_in) const {
;     ...
;                 for (int m = 0; m < 4; ++m) { const size_t off = (size_t)(row0 + ai * HALF + m * 16) * 1024 + col0 + bj * HALF; f32x4 b[2];
;                     if constexpr (BASE == 0) { b[0] = pf[m][0]; b[1] = pf[m][1]; }
;                     else { const u32x4 pw = pb[m]; b[0] = (f32x4){bf_lo(pw.x), bf_hi(pw.x), bf_lo(pw.y), bf_hi(pw.y)}; b[1] = (f32x4){bf_lo(pw.z), bf_hi(pw.z), bf_lo(pw.w), bf_hi(pw.w)}; }
;                     f32x4 z[2];
; #pragma unroll
;                     for (int n = 0; n < 2; ++n) { if constexpr (BASE == 1) b[n] = (b[n] - rst.mu[ai][m]) * rst.rs[ai][m] * gv[n] + bv[n];
;                         z[n] = b[n] * al_ + acc[ai][bj][m][n] * s_; }
;                     u32x4 w; w.x = cvt_pk_bf16(z[0][0], z[0][1]); w.y = cvt_pk_bf16(z[0][2], z[0][3]); w.z = cvt_pk_bf16(z[1][0], z[1][1]); w.w = cvt_pk_bf16(z[1][2], z[1][3]);
;                     *(u32x4*)(zb + off) = w;
;                     const float r0 = bf_lo(w.x), r1 = bf_hi(w.x), r2 = bf_lo(w.y), r3 = bf_hi(w.y), r4 = bf_lo(w.z), r5 = bf_hi(w.z), r6 = bf_lo(w.w), r7 = bf_hi(w.w);
;                     s1[ai][m] += ((r0 + r1) + (r2 + r3)) + ((r4 + r5) + (r6 + r7)); s2[ai][m] += ((r0 * r0 + r1 * r1) + (r2 * r2 + r3 * r3)) + ((r4 * r4 + r5 * r5) + (r6 * r6 + r7 * r7)); }
	v_and_b32_e32 v21, 0xffff0000, v102
	v_lshlrev_b32_e32 v22, 16, v103
	v_and_b32_e32 v23, 0xffff0000, v103
	v_pk_mul_f32 v[14:15], v[176:177], v[14:15] op_sel_hi:[0,1]
	v_pk_mul_f32 v[12:13], v[176:177], v[12:13] op_sel_hi:[0,1]
	v_pk_fma_f32 v[6:7], v[6:7], v[174:175], v[12:13] op_sel_hi:[1,0,1]
	v_pk_fma_f32 v[4:5], v[4:5], v[174:175], v[14:15] op_sel_hi:[1,0,1]
	v_sub_f32_e32 v13, v23, v180
	v_sub_f32_e32 v12, v22, v180
	v_sub_f32_e32 v15, v21, v180
	v_sub_f32_e32 v14, v20, v180
	v_pk_mul_f32 v[14:15], v[178:179], v[14:15] op_sel_hi:[0,1]
	v_pk_mul_f32 v[12:13], v[178:179], v[12:13] op_sel_hi:[0,1]
	v_pk_fma_f32 v[12:13], v[70:71], v[12:13], v[78:79]
	v_pk_fma_f32 v[14:15], v[68:69], v[14:15], v[76:77]
	v_pk_mul_f32 v[12:13], v[176:177], v[12:13] op_sel_hi:[0,1]
	v_pk_mul_f32 v[14:15], v[176:177], v[14:15] op_sel_hi:[0,1]
	v_pk_fma_f32 v[12:13], v[2:3], v[174:175], v[12:13] op_sel_hi:[1,0,1]
	v_pk_fma_f32 v[2:3], v[0:1], v[174:175], v[14:15] op_sel_hi:[1,0,1]
	v_cvt_pk_bf16_f32 v0, v4, v5
	v_and_b32_e32 v5, 64, v195
	v_xor_b32_e32 v4, 16, v195
	v_add_u32_e32 v5, 64, v5
	v_cmp_lt_i32_e32 vcc, v4, v5
	v_cvt_pk_bf16_f32 v2, v2, v3
	v_cvt_pk_bf16_f32 v3, v12, v13
	v_cvt_pk_bf16_f32 v1, v6, v7
	v_and_b32_e32 v21, 0xffff0000, v56
	v_and_b32_e32 v20, 0xffff0000, v121
	v_cndmask_b32_e32 v4, v195, v4, vcc
	v_lshlrev_b32_e32 v13, 2, v4
	v_xor_b32_e32 v4, 32, v195
	v_cmp_lt_i32_e32 vcc, v4, v5
	v_lshlrev_b32_e32 v5, 16, v56
	v_mov_b32_e32 v155, v5
	v_cndmask_b32_e32 v4, v195, v4, vcc
	v_lshlrev_b32_e32 v12, 2, v4
	v_lshlrev_b32_e32 v4, 16, v120
	v_pk_mul_f32 v[6:7], v[4:5], v[4:5]
	v_pk_mul_f32 v[14:15], v[154:155], v[154:155]
	v_mov_b32_e32 v153, v21
	v_pk_mov_b32 v[54:55], v[4:5], v[6:7] op_sel:[1,0]
	v_pk_add_f32 v[4:5], v[4:5], v[154:155]
	v_pk_mul_f32 v[22:23], v[152:153], v[152:153]
	v_pk_mul_f32 v[28:29], v[20:21], v[20:21]
	v_lshlrev_b32_e32 v30, 16, v122
	v_lshlrev_b32_e32 v31, 16, v57
	v_and_b32_e32 v45, 0xffff0000, v57
	v_and_b32_e32 v44, 0xffff0000, v123
	v_pk_mov_b32 v[14:15], v[20:21], v[14:15] op_sel:[1,0]
	v_mov_b32_e32 v5, v7
	v_pk_add_f32 v[6:7], v[20:21], v[152:153]
	v_mov_b32_e32 v127, v31
	v_mov_b32_e32 v125, v45
	v_pk_add_f32 v[14:15], v[54:55], v[14:15]
	v_pk_mov_b32 v[22:23], v[30:31], v[22:23] op_sel:[1,0]
	v_pk_mov_b32 v[54:55], v[44:45], v[28:29] op_sel:[1,0]
	v_mov_b32_e32 v7, v29
	v_pk_mul_f32 v[36:37], v[30:31], v[30:31]
	v_pk_mul_f32 v[38:39], v[126:127], v[126:127]
	v_pk_mul_f32 v[46:47], v[124:125], v[124:125]
	v_pk_mul_f32 v[52:53], v[44:45], v[44:45]
	v_pk_add_f32 v[22:23], v[22:23], v[54:55]
	v_pk_add_f32 v[4:5], v[4:5], v[6:7]
	v_pk_add_f32 v[6:7], v[30:31], v[126:127]
	v_pk_add_f32 v[20:21], v[44:45], v[124:125]
	v_pk_add_f32 v[14:15], v[14:15], v[22:23]
	v_mov_b32_e32 v22, v60
	v_mov_b32_e32 v23, v36
	v_mov_b32_e32 v54, v62
	v_mov_b32_e32 v55, v38
	v_pk_mov_b32 v[38:39], v[60:61], v[46:47] op_sel:[1,0]
	v_pk_mov_b32 v[46:47], v[62:63], v[52:53] op_sel:[1,0]
	v_mov_b32_e32 v7, v37
	v_mov_b32_e32 v21, v53
	v_pk_add_f32 v[22:23], v[22:23], v[54:55]
	v_pk_add_f32 v[38:39], v[38:39], v[46:47]
	v_pk_add_f32 v[6:7], v[6:7], v[20:21]
	v_pk_add_f32 v[22:23], v[22:23], v[38:39]
	v_pk_add_f32 v[4:5], v[4:5], v[6:7]
	v_pk_add_f32 v[14:15], v[14:15], v[22:23]
	v_pk_add_f32 v[4:5], v[4:5], v[164:165]
	global_store_dwordx4 v[144:145], v[24:27], off offset:256
	v_pk_add_f32 v[4:5], v[14:15], v[4:5]
	ds_bpermute_b32 v6, v13, v4
	ds_bpermute_b32 v7, v13, v5
	global_store_dwordx4 v[146:147], v[16:19], off offset:256
	global_store_dwordx4 v[150:151], v[8:11], off offset:256
	global_store_dwordx4 v[128:129], v[0:3], off offset:256
	s_waitcnt lgkmcnt(0)
	v_pk_add_f32 v[4:5], v[4:5], v[6:7]
	ds_bpermute_b32 v6, v12, v4
	ds_bpermute_b32 v7, v12, v5
	v_cmp_eq_u32_e32 vcc, 0, v203
	v_lshl_add_u32 v14, v199, 5, s66
	s_and_saveexec_b64 s[8:9], vcc
	s_cbranch_execz .LBB0_1367
	s_waitcnt lgkmcnt(0)
	v_pk_add_f32 v[4:5], v[4:5], v[6:7]
	ds_write_b64 v14, v[4:5]

; __device__ __forceinline__ void load_row_stats(const float* sp, int row0, RowStats& r) {
;     ...
;         for (int m = 0; m < 4; ++m) { const float* p = sp + (size_t)(row0 + ai * HALF + m * 16) * 8; const f32x4 a = *(const f32x4*)p, b = *(const f32x4*)(p + 4);
;             const float s1 = (a[0] + a[2]) + (b[0] + b[2]), s2 = (a[1] + a[3]) + (b[1] + b[3]); const float mu = s1 * (1.f / 1024.f); const float var = s2 * (1.f / 1024.f) - mu * mu;
;             r.mu[ai][m] = mu; r.rs[ai][m] = __builtin_amdgcn_rsqf(__builtin_fmaxf(var, 0.f) + 1e-5f); } }
;     __device__ __forceinline__ void operator()(const f32x4 (&acc)[2][2][4][2], const Unit& u, int wr, int wc, int fr_in, int fq_in) const {
;     ...
;         for (int bj = 0; bj < 2; ++bj) { f32x4 gv[2], bv[2];
;             if constexpr (BASE == 1) {
; #pragma unroll
;                 for (int n = 0; n < 2; ++n) { gv[n] = *(const f32x4*)(lg + col0 + bj * HALF + 4 * n); bv[n] = *(const f32x4*)(lb + col0 + bj * HALF + 4 * n); } }
; #pragma unroll
;             for (int ai = 0; ai < 2; ++ai) {
;                 f32x4 pf[4][2]; u32x4 pb[4];
; #pragma unroll
;                 for (int m = 0; m < 4; ++m) { const size_t off = (size_t)(row0 + ai * HALF + m * 16) * 1024 + col0 + bj * HALF;
;                     if constexpr (BASE == 0) { pf[m][0] = *(const f32x4*)(basef + off); pf[m][1] = *(const f32x4*)(basef + off + 4); } else pb[m] = *(const u32x4*)(baseb + off); }
.LBB0_1910:
	s_lshl_b32 s11, s48, 8
	v_mov_b32_e32 v199, v175
	v_mov_b32_e32 v203, v177
	s_add_i32 s8, s11, s60
	v_mov_b32_e32 v176, 0x3fb504f3
	v_add_u32_e32 v146, s8, v199
	v_ashrrev_i32_e32 v147, 31, v146
	v_mov_b32_e32 v174, 1.0
	v_add_u32_e32 v144, 16, v146
	v_ashrrev_i32_e32 v145, 31, v144
	v_add_u32_e32 v148, 32, v146
	v_ashrrev_i32_e32 v149, 31, v148
	v_add_u32_e32 v150, 48, v146
	v_ashrrev_i32_e32 v151, 31, v150
	v_add_u32_e32 v222, 0x80, v146
	v_ashrrev_i32_e32 v223, 31, v222
	v_add_u32_e32 v226, 0x90, v146
	v_ashrrev_i32_e32 v227, 31, v226
	v_add_u32_e32 v210, 0xa0, v146
	v_ashrrev_i32_e32 v211, 31, v210
	v_add_u32_e32 v212, 0xb0, v146
	v_ashrrev_i32_e32 v213, 31, v212
	s_lshl_b32 s8, s10, 8
	s_or_b32 s8, s8, s61
	v_lshl_add_u32 v152, v203, 3, s8
	v_ashrrev_i32_e32 v153, 31, v152
	v_lshlrev_b64 v[220:221], 1, v[152:153]
	v_lshl_add_u64 v[234:235], s[22:23], 0, v[220:221]
	v_lshlrev_b64 v[232:233], 11, v[146:147]
	v_lshl_add_u64 v[218:219], v[234:235], 0, v[232:233]
	v_lshlrev_b64 v[236:237], 11, v[144:145]
	v_lshl_add_u64 v[224:225], v[234:235], 0, v[236:237]
	v_lshlrev_b64 v[240:241], 11, v[148:149]
	v_lshl_add_u64 v[228:229], v[234:235], 0, v[240:241]
	v_lshlrev_b64 v[238:239], 11, v[150:151]
	v_lshl_add_u64 v[230:231], v[234:235], 0, v[238:239]
	v_and_b32_e32 v181, 0xff, v146
	v_lshlrev_b32_e32 v181, 3, v181
	v_add_u32_e32 v181, 0x22400, v181
	v_and_b32_e32 v208, 0xffffff00, v146
	v_lshlrev_b64 v[128:129], 2, v[152:153]
	v_lshl_add_u64 v[216:217], s[4:5], 0, v[128:129]
	v_lshl_add_u64 v[214:215], s[6:7], 0, v[128:129]
	global_load_dwordx4 v[128:131], v[216:217], off offset:16
	global_load_dwordx4 v[136:139], v[216:217], off
	global_load_dwordx4 v[132:135], v[214:215], off offset:16
	global_load_dwordx4 v[140:143], v[214:215], off
	global_load_dwordx4 v[152:155], v[218:219], off
	global_load_dwordx4 v[144:147], v[224:225], off
	global_load_dwordx4 v[242:245], v[228:229], off
	global_load_dwordx4 v[148:151], v[230:231], off
	v_readfirstlane_b32 s98, v254
	s_nop 0
	s_cmpk_lt_u32 s98, 0x100
	s_cbranch_scc0 .Lrs8_skip
	v_add_u32_e32 v208, v208, v254
	v_mov_b32_e32 v209, 0
	v_lshlrev_b64 v[208:209], 5, v[208:209]
	v_lshl_add_u64 v[208:209], s[24:25], 0, v[208:209]
	global_load_dwordx2 v[204:205], v[208:209], off
	global_load_dwordx2 v[200:201], v[208:209], off offset:8
	global_load_dwordx2 v[196:197], v[208:209], off offset:16
	global_load_dwordx2 v[192:193], v[208:209], off offset:24
	s_waitcnt vmcnt(0)
	v_pk_add_f32 v[196:197], v[196:197], v[192:193]
	v_pk_add_f32 v[204:205], v[204:205], v[200:201]
	s_nop 0
	v_pk_add_f32 v[196:197], v[204:205], v[196:197]
	s_nop 0
	v_pk_mul_f32 v[196:197], v[196:197], s[40:41] op_sel_hi:[1,0]
	v_lshlrev_b32_e32 v188, 3, v254
	v_add_u32_e32 v188, 0x22400, v188
	ds_write_b64 v188, v[196:197]

; __device__ __forceinline__ void load_row_stats(const float* sp, int row0, RowStats& r) {
;     ...
;         for (int m = 0; m < 4; ++m) { const float* p = sp + (size_t)(row0 + ai * HALF + m * 16) * 8; const f32x4 a = *(const f32x4*)p, b = *(const f32x4*)(p + 4);
;             const float s1 = (a[0] + a[2]) + (b[0] + b[2]), s2 = (a[1] + a[3]) + (b[1] + b[3]); const float mu = s1 * (1.f / 1024.f); const float var = s2 * (1.f / 1024.f) - mu * mu;
;             r.mu[ai][m] = mu; r.rs[ai][m] = __builtin_amdgcn_rsqf(__builtin_fmaxf(var, 0.f) + 1e-5f); } }
;     __device__ __forceinline__ void operator()(const f32x4 (&acc)[2][2][4][2], const Unit& u, int wr, int wc, int fr_in, int fq_in) const {
;     ...
;         for (int bj = 0; bj < 2; ++bj) { f32x4 gv[2], bv[2];
;             if constexpr (BASE == 1) {
; #pragma unroll
;                 for (int n = 0; n < 2; ++n) { gv[n] = *(const f32x4*)(lg + col0 + bj * HALF + 4 * n); bv[n] = *(const f32x4*)(lb + col0 + bj * HALF + 4 * n); } }
; #pragma unroll
;             for (int ai = 0; ai < 2; ++ai) {
;                 f32x4 pf[4][2]; u32x4 pb[4];
; #pragma unroll
;                 for (int m = 0; m < 4; ++m) { const size_t off = (size_t)(row0 + ai * HALF + m * 16) * 1024 + col0 + bj * HALF;
;                     if constexpr (BASE == 0) { pf[m][0] = *(const f32x4*)(basef + off); pf[m][1] = *(const f32x4*)(basef + off + 4); } else pb[m] = *(const u32x4*)(baseb + off); }
.LBB0_2100:
	s_lshl_b32 s11, s46, 8
	v_mov_b32_e32 v203, v177
	v_mov_b32_e32 v199, v175
	s_add_i32 s8, s11, s60
	v_mov_b32_e32 v174, 0.5
	v_add_u32_e32 v146, s8, v199
	v_ashrrev_i32_e32 v147, 31, v146
	v_mov_b32_e32 v176, 0x3fb504f3
	v_add_u32_e32 v144, 16, v146
	v_ashrrev_i32_e32 v145, 31, v144
	v_add_u32_e32 v148, 32, v146
	v_ashrrev_i32_e32 v149, 31, v148
	v_add_u32_e32 v150, 48, v146
	v_ashrrev_i32_e32 v151, 31, v150
	v_add_u32_e32 v222, 0x80, v146
	v_ashrrev_i32_e32 v223, 31, v222
	v_add_u32_e32 v226, 0x90, v146
	v_ashrrev_i32_e32 v227, 31, v226
	v_add_u32_e32 v210, 0xa0, v146
	v_ashrrev_i32_e32 v211, 31, v210
	v_add_u32_e32 v212, 0xb0, v146
	v_ashrrev_i32_e32 v213, 31, v212
	s_lshl_b32 s8, s10, 8
	s_or_b32 s8, s8, s61
	v_lshl_add_u32 v152, v203, 3, s8
	v_ashrrev_i32_e32 v153, 31, v152
	v_lshlrev_b64 v[220:221], 1, v[152:153]
	v_lshl_add_u64 v[234:235], s[26:27], 0, v[220:221]
	v_lshlrev_b64 v[232:233], 11, v[146:147]
	v_lshl_add_u64 v[218:219], v[234:235], 0, v[232:233]
	v_lshlrev_b64 v[236:237], 11, v[144:145]
	v_lshl_add_u64 v[224:225], v[234:235], 0, v[236:237]
	v_lshlrev_b64 v[240:241], 11, v[148:149]
	v_lshl_add_u64 v[228:229], v[234:235], 0, v[240:241]
	v_lshlrev_b64 v[238:239], 11, v[150:151]
	v_lshl_add_u64 v[230:231], v[234:235], 0, v[238:239]
	v_and_b32_e32 v181, 0xff, v146
	v_lshlrev_b32_e32 v181, 3, v181
	v_add_u32_e32 v181, 0x22400, v181
	v_and_b32_e32 v208, 0xffffff00, v146
	v_lshlrev_b64 v[128:129], 2, v[152:153]
	v_lshl_add_u64 v[216:217], s[4:5], 0, v[128:129]
	v_lshl_add_u64 v[214:215], s[6:7], 0, v[128:129]
	global_load_dwordx4 v[128:131], v[216:217], off offset:16
	global_load_dwordx4 v[136:139], v[216:217], off
	global_load_dwordx4 v[132:135], v[214:215], off offset:16
	global_load_dwordx4 v[140:143], v[214:215], off
	global_load_dwordx4 v[152:155], v[218:219], off
	global_load_dwordx4 v[144:147], v[224:225], off
	global_load_dwordx4 v[242:245], v[228:229], off
	global_load_dwordx4 v[148:151], v[230:231], off
	v_readfirstlane_b32 s98, v254
	s_nop 0
	s_cmpk_lt_u32 s98, 0x100
	s_cbranch_scc0 .Lrs10_skip
	v_add_u32_e32 v208, v208, v254
	v_mov_b32_e32 v209, 0
	v_lshlrev_b64 v[208:209], 5, v[208:209]
	v_lshl_add_u64 v[208:209], s[22:23], 0, v[208:209]
	global_load_dwordx2 v[204:205], v[208:209], off
	global_load_dwordx2 v[200:201], v[208:209], off offset:8
	global_load_dwordx2 v[196:197], v[208:209], off offset:16
	global_load_dwordx2 v[192:193], v[208:209], off offset:24
	s_waitcnt vmcnt(0)
	v_pk_add_f32 v[196:197], v[196:197], v[192:193]
	v_pk_add_f32 v[204:205], v[204:205], v[200:201]
	s_nop 0
	v_pk_add_f32 v[196:197], v[204:205], v[196:197]
	s_nop 0
	v_pk_mul_f32 v[196:197], v[196:197], s[34:35] op_sel_hi:[1,0]
	v_lshlrev_b32_e32 v188, 3, v254
	v_add_u32_e32 v188, 0x22400, v188
	ds_write_b64 v188, v[196:197]
